# SSD gate fused into the mixer phase, now software-pipelined: 8 passes of YF/YB/z loads in flight with counted vmcnt, fully unrolled 16 passes
# baseline (speedup 1.0000x reference)
.Lsg_go:
	v_mov_b32_e32 v30, v2
	v_add_u32_e32 v1, s8, v1
	v_lshl_add_u32 v2, v2, 3, s10
	v_lshlrev_b32_e32 v3, 2, v2
	global_load_dwordx4 v[14:17], v3, s[6:7]
	global_load_dwordx4 v[18:21], v3, s[6:7] offset:16
	v_lshlrev_b32_e32 v2, 1, v2
	v_mov_b32_e32 v3, 0
	v_mov_b32_e32 v22, v1
	v_mov_b32_e32 v23, 0
	v_lshlrev_b64 v[4:5], 11, v[22:23]
	v_lshl_add_u64 v[4:5], v[4:5], 0, s[14:15]
	v_lshl_add_u64 v[4:5], v[4:5], 0, v[2:3]
	v_lshlrev_b64 v[6:7], 11, v[22:23]
	v_lshl_add_u64 v[6:7], v[6:7], 0, s[16:17]
	v_lshl_add_u64 v[6:7], v[6:7], 0, v[2:3]
	v_mul_u32_u24_e32 v24, 0x2c00, v1
	v_mov_b32_e32 v25, 0
	v_lshl_add_u64 v[8:9], v[24:25], 0, s[18:19]
	v_lshl_add_u64 v[8:9], v[8:9], 0, v[2:3]
	v_lshlrev_b64 v[10:11], 12, v[22:23]
	v_lshl_add_u64 v[10:11], v[10:11], 0, s[20:21]
	v_lshl_add_u64 v[10:11], v[10:11], 0, v[2:3]
	s_lshl_b32 s13, s11, 2
	s_add_u32 s48, s22, s13
	s_addc_u32 s49, s23, 0
	v_lshlrev_b64 v[12:13], 6, v[22:23]
	v_lshl_add_u64 v[12:13], v[12:13], 0, s[48:49]
	s_lshl_b32 s28, s12, 11
	s_mov_b32 s29, 0
	s_mul_i32 s34, s12, 0x2c00
	s_mov_b32 s35, 0
	s_lshl_b32 s38, s12, 12
	s_mov_b32 s39, 0
	s_lshl_b32 s40, s12, 6
	s_mov_b32 s41, 0
	global_load_dwordx4 v[48:51], v[4:5], off
	global_load_dwordx4 v[52:55], v[6:7], off
	global_load_dwordx4 v[56:59], v[8:9], off
	v_lshl_add_u64 v[4:5], v[4:5], 0, s[28:29]
	v_lshl_add_u64 v[6:7], v[6:7], 0, s[28:29]
	v_lshl_add_u64 v[8:9], v[8:9], 0, s[34:35]
	global_load_dwordx4 v[60:63], v[4:5], off
	global_load_dwordx4 v[64:67], v[6:7], off
	global_load_dwordx4 v[68:71], v[8:9], off
	v_lshl_add_u64 v[4:5], v[4:5], 0, s[28:29]
	v_lshl_add_u64 v[6:7], v[6:7], 0, s[28:29]
	v_lshl_add_u64 v[8:9], v[8:9], 0, s[34:35]
	global_load_dwordx4 v[72:75], v[4:5], off
	global_load_dwordx4 v[76:79], v[6:7], off
	global_load_dwordx4 v[80:83], v[8:9], off
	v_lshl_add_u64 v[4:5], v[4:5], 0, s[28:29]
	v_lshl_add_u64 v[6:7], v[6:7], 0, s[28:29]
	v_lshl_add_u64 v[8:9], v[8:9], 0, s[34:35]
	global_load_dwordx4 v[84:87], v[4:5], off
	global_load_dwordx4 v[88:91], v[6:7], off
	global_load_dwordx4 v[92:95], v[8:9], off
	v_lshl_add_u64 v[4:5], v[4:5], 0, s[28:29]
	v_lshl_add_u64 v[6:7], v[6:7], 0, s[28:29]
	v_lshl_add_u64 v[8:9], v[8:9], 0, s[34:35]
	global_load_dwordx4 v[96:99], v[4:5], off
	global_load_dwordx4 v[100:103], v[6:7], off
	global_load_dwordx4 v[104:107], v[8:9], off
	v_lshl_add_u64 v[4:5], v[4:5], 0, s[28:29]
	v_lshl_add_u64 v[6:7], v[6:7], 0, s[28:29]
	v_lshl_add_u64 v[8:9], v[8:9], 0, s[34:35]
	global_load_dwordx4 v[108:111], v[4:5], off
	global_load_dwordx4 v[112:115], v[6:7], off
	global_load_dwordx4 v[116:119], v[8:9], off
	v_lshl_add_u64 v[4:5], v[4:5], 0, s[28:29]
	v_lshl_add_u64 v[6:7], v[6:7], 0, s[28:29]
	v_lshl_add_u64 v[8:9], v[8:9], 0, s[34:35]
	global_load_dwordx4 v[120:123], v[4:5], off
	global_load_dwordx4 v[124:127], v[6:7], off
	global_load_dwordx4 v[128:131], v[8:9], off
	v_lshl_add_u64 v[4:5], v[4:5], 0, s[28:29]
	v_lshl_add_u64 v[6:7], v[6:7], 0, s[28:29]
	v_lshl_add_u64 v[8:9], v[8:9], 0, s[34:35]
	global_load_dwordx4 v[132:135], v[4:5], off
	global_load_dwordx4 v[136:139], v[6:7], off
	global_load_dwordx4 v[140:143], v[8:9], off
	v_lshl_add_u64 v[4:5], v[4:5], 0, s[28:29]
	v_lshl_add_u64 v[6:7], v[6:7], 0, s[28:29]
	v_lshl_add_u64 v[8:9], v[8:9], 0, s[34:35]
	s_waitcnt vmcnt(21)
	v_mov_b32_e32 v26, 0
	v_lshlrev_b32_e32 v32, 16, v48
	v_and_b32_e32 v33, 0xffff0000, v48
	v_lshlrev_b32_e32 v34, 16, v52
	v_and_b32_e32 v35, 0xffff0000, v52
	v_lshlrev_b32_e32 v36, 16, v56
	v_and_b32_e32 v37, 0xffff0000, v56
	v_add_f32_e32 v32, v32, v34
	v_add_f32_e32 v33, v33, v35
	v_mul_f32_e32 v38, 0xbfb8aa3b, v36
	v_mul_f32_e32 v39, 0xbfb8aa3b, v37
	v_exp_f32_e32 v38, v38
	v_exp_f32_e32 v39, v39
	s_nop 0
	v_add_f32_e32 v38, 1.0, v38
	v_add_f32_e32 v39, 1.0, v39
	v_rcp_f32_e32 v38, v38
	v_rcp_f32_e32 v39, v39
	s_nop 0
	v_mul_f32_e32 v38, v36, v38
	v_mul_f32_e32 v39, v37, v39
	v_mul_f32_e32 v32, v32, v38
	v_mul_f32_e32 v33, v33, v39
	v_fmac_f32_e32 v26, v32, v32
	v_fmac_f32_e32 v26, v33, v33
	v_mul_f32_e32 v32, v32, v14
	v_mul_f32_e32 v33, v33, v15
	v_cvt_pk_bf16_f32 v40, v32, v33
	v_lshlrev_b32_e32 v32, 16, v49
	v_and_b32_e32 v33, 0xffff0000, v49
	v_lshlrev_b32_e32 v34, 16, v53
	v_and_b32_e32 v35, 0xffff0000, v53
	v_lshlrev_b32_e32 v36, 16, v57
	v_and_b32_e32 v37, 0xffff0000, v57
	v_add_f32_e32 v32, v32, v34
	v_add_f32_e32 v33, v33, v35
	v_mul_f32_e32 v38, 0xbfb8aa3b, v36
	v_mul_f32_e32 v39, 0xbfb8aa3b, v37
	v_exp_f32_e32 v38, v38
	v_exp_f32_e32 v39, v39
	s_nop 0
	v_add_f32_e32 v38, 1.0, v38
	v_add_f32_e32 v39, 1.0, v39
	v_rcp_f32_e32 v38, v38
	v_rcp_f32_e32 v39, v39
	s_nop 0
	v_mul_f32_e32 v38, v36, v38
	v_mul_f32_e32 v39, v37, v39
	v_mul_f32_e32 v32, v32, v38
	v_mul_f32_e32 v33, v33, v39
	v_fmac_f32_e32 v26, v32, v32
	v_fmac_f32_e32 v26, v33, v33
	v_mul_f32_e32 v32, v32, v16
	v_mul_f32_e32 v33, v33, v17
	v_cvt_pk_bf16_f32 v41, v32, v33
	v_lshlrev_b32_e32 v32, 16, v50
	v_and_b32_e32 v33, 0xffff0000, v50
	v_lshlrev_b32_e32 v34, 16, v54
	v_and_b32_e32 v35, 0xffff0000, v54
	v_lshlrev_b32_e32 v36, 16, v58
	v_and_b32_e32 v37, 0xffff0000, v58
	v_add_f32_e32 v32, v32, v34
	v_add_f32_e32 v33, v33, v35
	v_mul_f32_e32 v38, 0xbfb8aa3b, v36
	v_mul_f32_e32 v39, 0xbfb8aa3b, v37
	v_exp_f32_e32 v38, v38
	v_exp_f32_e32 v39, v39
	s_nop 0
	v_add_f32_e32 v38, 1.0, v38
	v_add_f32_e32 v39, 1.0, v39
	v_rcp_f32_e32 v38, v38
	v_rcp_f32_e32 v39, v39
	s_nop 0
	v_mul_f32_e32 v38, v36, v38
	v_mul_f32_e32 v39, v37, v39
	v_mul_f32_e32 v32, v32, v38
	v_mul_f32_e32 v33, v33, v39
	v_fmac_f32_e32 v26, v32, v32
	v_fmac_f32_e32 v26, v33, v33
	v_mul_f32_e32 v32, v32, v18
	v_mul_f32_e32 v33, v33, v19
	v_cvt_pk_bf16_f32 v42, v32, v33
	v_lshlrev_b32_e32 v32, 16, v51
	v_and_b32_e32 v33, 0xffff0000, v51
	v_lshlrev_b32_e32 v34, 16, v55
	v_and_b32_e32 v35, 0xffff0000, v55
	v_lshlrev_b32_e32 v36, 16, v59
	v_and_b32_e32 v37, 0xffff0000, v59
	v_add_f32_e32 v32, v32, v34
	v_add_f32_e32 v33, v33, v35
	v_mul_f32_e32 v38, 0xbfb8aa3b, v36
	v_mul_f32_e32 v39, 0xbfb8aa3b, v37
	v_exp_f32_e32 v38, v38
	v_exp_f32_e32 v39, v39
	s_nop 0
	v_add_f32_e32 v38, 1.0, v38
	v_add_f32_e32 v39, 1.0, v39
	v_rcp_f32_e32 v38, v38
	v_rcp_f32_e32 v39, v39
	s_nop 0
	v_mul_f32_e32 v38, v36, v38
	v_mul_f32_e32 v39, v37, v39
	v_mul_f32_e32 v32, v32, v38
	v_mul_f32_e32 v33, v33, v39
	v_fmac_f32_e32 v26, v32, v32
	v_fmac_f32_e32 v26, v33, v33
	v_mul_f32_e32 v32, v32, v20
	v_mul_f32_e32 v33, v33, v21
	v_cvt_pk_bf16_f32 v43, v32, v33
	global_load_dwordx4 v[48:51], v[4:5], off
	global_load_dwordx4 v[52:55], v[6:7], off
	global_load_dwordx4 v[56:59], v[8:9], off
	v_lshl_add_u64 v[4:5], v[4:5], 0, s[28:29]
	v_lshl_add_u64 v[6:7], v[6:7], 0, s[28:29]
	v_lshl_add_u64 v[8:9], v[8:9], 0, s[34:35]
	global_store_dwordx4 v[10:11], v[40:43], off
	s_nop 1
	v_add_f32_dpp v26, v26, v26 quad_perm:[1,0,3,2] row_mask:0xf bank_mask:0xf bound_ctrl:1
	s_nop 1
	v_add_f32_dpp v26, v26, v26 quad_perm:[2,3,0,1] row_mask:0xf bank_mask:0xf bound_ctrl:1
	s_nop 1
	v_add_f32_dpp v26, v26, v26 row_half_mirror row_mask:0xf bank_mask:0xf bound_ctrl:1
	s_cmp_eq_u32 s12, 64
	s_cbranch_scc1 .Lsg_red_done_0
	s_nop 1
	v_add_f32_dpp v26, v26, v26 row_mirror row_mask:0xf bank_mask:0xf bound_ctrl:1
	v_mov_b32_e32 v31, v26
	s_nop 1
	v_permlane16_swap_b32_e32 v26, v31
	v_add_f32_e32 v26, v26, v31
.Lsg_red_done_0:
	v_mov_b32_e32 v27, 0
	v_mov_b32_e32 v28, 0
	v_mov_b32_e32 v29, 0
	v_cmp_eq_u32_e32 vcc, 0, v30
	s_and_saveexec_b64 s[42:43], vcc
	s_cmp_eq_u32 s12, 64
	s_cbranch_scc0 .Lsg_st4_0
	global_store_dword v[12:13], v26, off
	s_branch .Lsg_st_done_0
.Lsg_st4_0:
	global_store_dwordx4 v[12:13], v[26:29], off
.Lsg_st_done_0:
	s_or_b64 exec, exec, s[42:43]
	v_lshl_add_u64 v[10:11], v[10:11], 0, s[38:39]
	v_lshl_add_u64 v[12:13], v[12:13], 0, s[40:41]
	s_waitcnt vmcnt(23)
	v_mov_b32_e32 v26, 0
	v_lshlrev_b32_e32 v32, 16, v60
	v_and_b32_e32 v33, 0xffff0000, v60
	v_lshlrev_b32_e32 v34, 16, v64
	v_and_b32_e32 v35, 0xffff0000, v64
	v_lshlrev_b32_e32 v36, 16, v68
	v_and_b32_e32 v37, 0xffff0000, v68
	v_add_f32_e32 v32, v32, v34
	v_add_f32_e32 v33, v33, v35
	v_mul_f32_e32 v38, 0xbfb8aa3b, v36
	v_mul_f32_e32 v39, 0xbfb8aa3b, v37
	v_exp_f32_e32 v38, v38
	v_exp_f32_e32 v39, v39
	s_nop 0
	v_add_f32_e32 v38, 1.0, v38
	v_add_f32_e32 v39, 1.0, v39
	v_rcp_f32_e32 v38, v38
	v_rcp_f32_e32 v39, v39
	s_nop 0
	v_mul_f32_e32 v38, v36, v38
	v_mul_f32_e32 v39, v37, v39
	v_mul_f32_e32 v32, v32, v38
	v_mul_f32_e32 v33, v33, v39
	v_fmac_f32_e32 v26, v32, v32
	v_fmac_f32_e32 v26, v33, v33
	v_mul_f32_e32 v32, v32, v14
	v_mul_f32_e32 v33, v33, v15
	v_cvt_pk_bf16_f32 v40, v32, v33
	v_lshlrev_b32_e32 v32, 16, v61
	v_and_b32_e32 v33, 0xffff0000, v61
	v_lshlrev_b32_e32 v34, 16, v65
	v_and_b32_e32 v35, 0xffff0000, v65
	v_lshlrev_b32_e32 v36, 16, v69
	v_and_b32_e32 v37, 0xffff0000, v69
	v_add_f32_e32 v32, v32, v34
	v_add_f32_e32 v33, v33, v35
	v_mul_f32_e32 v38, 0xbfb8aa3b, v36
	v_mul_f32_e32 v39, 0xbfb8aa3b, v37
	v_exp_f32_e32 v38, v38
	v_exp_f32_e32 v39, v39
	s_nop 0
	v_add_f32_e32 v38, 1.0, v38
	v_add_f32_e32 v39, 1.0, v39
	v_rcp_f32_e32 v38, v38
	v_rcp_f32_e32 v39, v39
	s_nop 0
	v_mul_f32_e32 v38, v36, v38
	v_mul_f32_e32 v39, v37, v39
	v_mul_f32_e32 v32, v32, v38
	v_mul_f32_e32 v33, v33, v39
	v_fmac_f32_e32 v26, v32, v32
	v_fmac_f32_e32 v26, v33, v33
	v_mul_f32_e32 v32, v32, v16
	v_mul_f32_e32 v33, v33, v17
	v_cvt_pk_bf16_f32 v41, v32, v33
	v_lshlrev_b32_e32 v32, 16, v62
	v_and_b32_e32 v33, 0xffff0000, v62
	v_lshlrev_b32_e32 v34, 16, v66
	v_and_b32_e32 v35, 0xffff0000, v66
	v_lshlrev_b32_e32 v36, 16, v70
	v_and_b32_e32 v37, 0xffff0000, v70
	v_add_f32_e32 v32, v32, v34
	v_add_f32_e32 v33, v33, v35
	v_mul_f32_e32 v38, 0xbfb8aa3b, v36
	v_mul_f32_e32 v39, 0xbfb8aa3b, v37
	v_exp_f32_e32 v38, v38
	v_exp_f32_e32 v39, v39
	s_nop 0
	v_add_f32_e32 v38, 1.0, v38
	v_add_f32_e32 v39, 1.0, v39
	v_rcp_f32_e32 v38, v38
	v_rcp_f32_e32 v39, v39
	s_nop 0
	v_mul_f32_e32 v38, v36, v38
	v_mul_f32_e32 v39, v37, v39
	v_mul_f32_e32 v32, v32, v38
	v_mul_f32_e32 v33, v33, v39
	v_fmac_f32_e32 v26, v32, v32
	v_fmac_f32_e32 v26, v33, v33
	v_mul_f32_e32 v32, v32, v18
	v_mul_f32_e32 v33, v33, v19
	v_cvt_pk_bf16_f32 v42, v32, v33
	v_lshlrev_b32_e32 v32, 16, v63
	v_and_b32_e32 v33, 0xffff0000, v63
	v_lshlrev_b32_e32 v34, 16, v67
	v_and_b32_e32 v35, 0xffff0000, v67
	v_lshlrev_b32_e32 v36, 16, v71
	v_and_b32_e32 v37, 0xffff0000, v71
	v_add_f32_e32 v32, v32, v34
	v_add_f32_e32 v33, v33, v35
	v_mul_f32_e32 v38, 0xbfb8aa3b, v36
	v_mul_f32_e32 v39, 0xbfb8aa3b, v37
	v_exp_f32_e32 v38, v38
	v_exp_f32_e32 v39, v39
	s_nop 0
	v_add_f32_e32 v38, 1.0, v38
	v_add_f32_e32 v39, 1.0, v39
	v_rcp_f32_e32 v38, v38
	v_rcp_f32_e32 v39, v39
	s_nop 0
	v_mul_f32_e32 v38, v36, v38
	v_mul_f32_e32 v39, v37, v39
	v_mul_f32_e32 v32, v32, v38
	v_mul_f32_e32 v33, v33, v39
	v_fmac_f32_e32 v26, v32, v32
	v_fmac_f32_e32 v26, v33, v33
	v_mul_f32_e32 v32, v32, v20
	v_mul_f32_e32 v33, v33, v21
	v_cvt_pk_bf16_f32 v43, v32, v33
	global_load_dwordx4 v[60:63], v[4:5], off
	global_load_dwordx4 v[64:67], v[6:7], off
	global_load_dwordx4 v[68:71], v[8:9], off
	v_lshl_add_u64 v[4:5], v[4:5], 0, s[28:29]
	v_lshl_add_u64 v[6:7], v[6:7], 0, s[28:29]
	v_lshl_add_u64 v[8:9], v[8:9], 0, s[34:35]
	global_store_dwordx4 v[10:11], v[40:43], off
	s_nop 1
	v_add_f32_dpp v26, v26, v26 quad_perm:[1,0,3,2] row_mask:0xf bank_mask:0xf bound_ctrl:1
	s_nop 1
	v_add_f32_dpp v26, v26, v26 quad_perm:[2,3,0,1] row_mask:0xf bank_mask:0xf bound_ctrl:1
	s_nop 1
	v_add_f32_dpp v26, v26, v26 row_half_mirror row_mask:0xf bank_mask:0xf bound_ctrl:1
	s_cmp_eq_u32 s12, 64
	s_cbranch_scc1 .Lsg_red_done_1
	s_nop 1
	v_add_f32_dpp v26, v26, v26 row_mirror row_mask:0xf bank_mask:0xf bound_ctrl:1
	v_mov_b32_e32 v31, v26
	s_nop 1
	v_permlane16_swap_b32_e32 v26, v31
	v_add_f32_e32 v26, v26, v31

.Lsg_st_done_1:
	s_or_b64 exec, exec, s[42:43]
	v_lshl_add_u64 v[10:11], v[10:11], 0, s[38:39]
	v_lshl_add_u64 v[12:13], v[12:13], 0, s[40:41]
	s_waitcnt vmcnt(25)
	v_mov_b32_e32 v26, 0
	v_lshlrev_b32_e32 v32, 16, v72
	v_and_b32_e32 v33, 0xffff0000, v72
	v_lshlrev_b32_e32 v34, 16, v76
	v_and_b32_e32 v35, 0xffff0000, v76
	v_lshlrev_b32_e32 v36, 16, v80
	v_and_b32_e32 v37, 0xffff0000, v80
	v_add_f32_e32 v32, v32, v34
	v_add_f32_e32 v33, v33, v35
	v_mul_f32_e32 v38, 0xbfb8aa3b, v36
	v_mul_f32_e32 v39, 0xbfb8aa3b, v37
	v_exp_f32_e32 v38, v38
	v_exp_f32_e32 v39, v39
	s_nop 0
	v_add_f32_e32 v38, 1.0, v38
	v_add_f32_e32 v39, 1.0, v39
	v_rcp_f32_e32 v38, v38
	v_rcp_f32_e32 v39, v39
	s_nop 0
	v_mul_f32_e32 v38, v36, v38
	v_mul_f32_e32 v39, v37, v39
	v_mul_f32_e32 v32, v32, v38
	v_mul_f32_e32 v33, v33, v39
	v_fmac_f32_e32 v26, v32, v32
	v_fmac_f32_e32 v26, v33, v33
	v_mul_f32_e32 v32, v32, v14
	v_mul_f32_e32 v33, v33, v15
	v_cvt_pk_bf16_f32 v40, v32, v33
	v_lshlrev_b32_e32 v32, 16, v73
	v_and_b32_e32 v33, 0xffff0000, v73
	v_lshlrev_b32_e32 v34, 16, v77
	v_and_b32_e32 v35, 0xffff0000, v77
	v_lshlrev_b32_e32 v36, 16, v81
	v_and_b32_e32 v37, 0xffff0000, v81
	v_add_f32_e32 v32, v32, v34
	v_add_f32_e32 v33, v33, v35
	v_mul_f32_e32 v38, 0xbfb8aa3b, v36
	v_mul_f32_e32 v39, 0xbfb8aa3b, v37
	v_exp_f32_e32 v38, v38
	v_exp_f32_e32 v39, v39
	s_nop 0
	v_add_f32_e32 v38, 1.0, v38
	v_add_f32_e32 v39, 1.0, v39
	v_rcp_f32_e32 v38, v38
	v_rcp_f32_e32 v39, v39
	s_nop 0
	v_mul_f32_e32 v38, v36, v38
	v_mul_f32_e32 v39, v37, v39
	v_mul_f32_e32 v32, v32, v38
	v_mul_f32_e32 v33, v33, v39
	v_fmac_f32_e32 v26, v32, v32
	v_fmac_f32_e32 v26, v33, v33
	v_mul_f32_e32 v32, v32, v16
	v_mul_f32_e32 v33, v33, v17
	v_cvt_pk_bf16_f32 v41, v32, v33
	v_lshlrev_b32_e32 v32, 16, v74
	v_and_b32_e32 v33, 0xffff0000, v74
	v_lshlrev_b32_e32 v34, 16, v78
	v_and_b32_e32 v35, 0xffff0000, v78
	v_lshlrev_b32_e32 v36, 16, v82
	v_and_b32_e32 v37, 0xffff0000, v82
	v_add_f32_e32 v32, v32, v34
	v_add_f32_e32 v33, v33, v35
	v_mul_f32_e32 v38, 0xbfb8aa3b, v36
	v_mul_f32_e32 v39, 0xbfb8aa3b, v37
	v_exp_f32_e32 v38, v38
	v_exp_f32_e32 v39, v39
	s_nop 0
	v_add_f32_e32 v38, 1.0, v38
	v_add_f32_e32 v39, 1.0, v39
	v_rcp_f32_e32 v38, v38
	v_rcp_f32_e32 v39, v39
	s_nop 0
	v_mul_f32_e32 v38, v36, v38
	v_mul_f32_e32 v39, v37, v39
	v_mul_f32_e32 v32, v32, v38
	v_mul_f32_e32 v33, v33, v39
	v_fmac_f32_e32 v26, v32, v32
	v_fmac_f32_e32 v26, v33, v33
	v_mul_f32_e32 v32, v32, v18
	v_mul_f32_e32 v33, v33, v19
	v_cvt_pk_bf16_f32 v42, v32, v33
	v_lshlrev_b32_e32 v32, 16, v75
	v_and_b32_e32 v33, 0xffff0000, v75
	v_lshlrev_b32_e32 v34, 16, v79
	v_and_b32_e32 v35, 0xffff0000, v79
	v_lshlrev_b32_e32 v36, 16, v83
	v_and_b32_e32 v37, 0xffff0000, v83
	v_add_f32_e32 v32, v32, v34
	v_add_f32_e32 v33, v33, v35
	v_mul_f32_e32 v38, 0xbfb8aa3b, v36
	v_mul_f32_e32 v39, 0xbfb8aa3b, v37
	v_exp_f32_e32 v38, v38
	v_exp_f32_e32 v39, v39
	s_nop 0
	v_add_f32_e32 v38, 1.0, v38
	v_add_f32_e32 v39, 1.0, v39
	v_rcp_f32_e32 v38, v38
	v_rcp_f32_e32 v39, v39
	s_nop 0
	v_mul_f32_e32 v38, v36, v38
	v_mul_f32_e32 v39, v37, v39
	v_mul_f32_e32 v32, v32, v38
	v_mul_f32_e32 v33, v33, v39
	v_fmac_f32_e32 v26, v32, v32
	v_fmac_f32_e32 v26, v33, v33
	v_mul_f32_e32 v32, v32, v20
	v_mul_f32_e32 v33, v33, v21
	v_cvt_pk_bf16_f32 v43, v32, v33
	global_load_dwordx4 v[72:75], v[4:5], off
	global_load_dwordx4 v[76:79], v[6:7], off
	global_load_dwordx4 v[80:83], v[8:9], off
	v_lshl_add_u64 v[4:5], v[4:5], 0, s[28:29]
	v_lshl_add_u64 v[6:7], v[6:7], 0, s[28:29]
	v_lshl_add_u64 v[8:9], v[8:9], 0, s[34:35]
	global_store_dwordx4 v[10:11], v[40:43], off
	s_nop 1
	v_add_f32_dpp v26, v26, v26 quad_perm:[1,0,3,2] row_mask:0xf bank_mask:0xf bound_ctrl:1
	s_nop 1
	v_add_f32_dpp v26, v26, v26 quad_perm:[2,3,0,1] row_mask:0xf bank_mask:0xf bound_ctrl:1
	s_nop 1
	v_add_f32_dpp v26, v26, v26 row_half_mirror row_mask:0xf bank_mask:0xf bound_ctrl:1
	s_cmp_eq_u32 s12, 64
	s_cbranch_scc1 .Lsg_red_done_2
	s_nop 1
	v_add_f32_dpp v26, v26, v26 row_mirror row_mask:0xf bank_mask:0xf bound_ctrl:1
	v_mov_b32_e32 v31, v26
	s_nop 1
	v_permlane16_swap_b32_e32 v26, v31
	v_add_f32_e32 v26, v26, v31

.Lsg_st_done_2:
	s_or_b64 exec, exec, s[42:43]
	v_lshl_add_u64 v[10:11], v[10:11], 0, s[38:39]
	v_lshl_add_u64 v[12:13], v[12:13], 0, s[40:41]
	s_waitcnt vmcnt(27)
	v_mov_b32_e32 v26, 0
	v_lshlrev_b32_e32 v32, 16, v84
	v_and_b32_e32 v33, 0xffff0000, v84
	v_lshlrev_b32_e32 v34, 16, v88
	v_and_b32_e32 v35, 0xffff0000, v88
	v_lshlrev_b32_e32 v36, 16, v92
	v_and_b32_e32 v37, 0xffff0000, v92
	v_add_f32_e32 v32, v32, v34
	v_add_f32_e32 v33, v33, v35
	v_mul_f32_e32 v38, 0xbfb8aa3b, v36
	v_mul_f32_e32 v39, 0xbfb8aa3b, v37
	v_exp_f32_e32 v38, v38
	v_exp_f32_e32 v39, v39
	s_nop 0
	v_add_f32_e32 v38, 1.0, v38
	v_add_f32_e32 v39, 1.0, v39
	v_rcp_f32_e32 v38, v38
	v_rcp_f32_e32 v39, v39
	s_nop 0
	v_mul_f32_e32 v38, v36, v38
	v_mul_f32_e32 v39, v37, v39
	v_mul_f32_e32 v32, v32, v38
	v_mul_f32_e32 v33, v33, v39
	v_fmac_f32_e32 v26, v32, v32
	v_fmac_f32_e32 v26, v33, v33
	v_mul_f32_e32 v32, v32, v14
	v_mul_f32_e32 v33, v33, v15
	v_cvt_pk_bf16_f32 v40, v32, v33
	v_lshlrev_b32_e32 v32, 16, v85
	v_and_b32_e32 v33, 0xffff0000, v85
	v_lshlrev_b32_e32 v34, 16, v89
	v_and_b32_e32 v35, 0xffff0000, v89
	v_lshlrev_b32_e32 v36, 16, v93
	v_and_b32_e32 v37, 0xffff0000, v93
	v_add_f32_e32 v32, v32, v34
	v_add_f32_e32 v33, v33, v35
	v_mul_f32_e32 v38, 0xbfb8aa3b, v36
	v_mul_f32_e32 v39, 0xbfb8aa3b, v37
	v_exp_f32_e32 v38, v38
	v_exp_f32_e32 v39, v39
	s_nop 0
	v_add_f32_e32 v38, 1.0, v38
	v_add_f32_e32 v39, 1.0, v39
	v_rcp_f32_e32 v38, v38
	v_rcp_f32_e32 v39, v39
	s_nop 0
	v_mul_f32_e32 v38, v36, v38
	v_mul_f32_e32 v39, v37, v39
	v_mul_f32_e32 v32, v32, v38
	v_mul_f32_e32 v33, v33, v39
	v_fmac_f32_e32 v26, v32, v32
	v_fmac_f32_e32 v26, v33, v33
	v_mul_f32_e32 v32, v32, v16
	v_mul_f32_e32 v33, v33, v17
	v_cvt_pk_bf16_f32 v41, v32, v33
	v_lshlrev_b32_e32 v32, 16, v86
	v_and_b32_e32 v33, 0xffff0000, v86
	v_lshlrev_b32_e32 v34, 16, v90
	v_and_b32_e32 v35, 0xffff0000, v90
	v_lshlrev_b32_e32 v36, 16, v94
	v_and_b32_e32 v37, 0xffff0000, v94
	v_add_f32_e32 v32, v32, v34
	v_add_f32_e32 v33, v33, v35
	v_mul_f32_e32 v38, 0xbfb8aa3b, v36
	v_mul_f32_e32 v39, 0xbfb8aa3b, v37
	v_exp_f32_e32 v38, v38
	v_exp_f32_e32 v39, v39
	s_nop 0
	v_add_f32_e32 v38, 1.0, v38
	v_add_f32_e32 v39, 1.0, v39
	v_rcp_f32_e32 v38, v38
	v_rcp_f32_e32 v39, v39
	s_nop 0
	v_mul_f32_e32 v38, v36, v38
	v_mul_f32_e32 v39, v37, v39
	v_mul_f32_e32 v32, v32, v38
	v_mul_f32_e32 v33, v33, v39
	v_fmac_f32_e32 v26, v32, v32
	v_fmac_f32_e32 v26, v33, v33
	v_mul_f32_e32 v32, v32, v18
	v_mul_f32_e32 v33, v33, v19
	v_cvt_pk_bf16_f32 v42, v32, v33
	v_lshlrev_b32_e32 v32, 16, v87
	v_and_b32_e32 v33, 0xffff0000, v87
	v_lshlrev_b32_e32 v34, 16, v91
	v_and_b32_e32 v35, 0xffff0000, v91
	v_lshlrev_b32_e32 v36, 16, v95
	v_and_b32_e32 v37, 0xffff0000, v95
	v_add_f32_e32 v32, v32, v34
	v_add_f32_e32 v33, v33, v35
	v_mul_f32_e32 v38, 0xbfb8aa3b, v36
	v_mul_f32_e32 v39, 0xbfb8aa3b, v37
	v_exp_f32_e32 v38, v38
	v_exp_f32_e32 v39, v39
	s_nop 0
	v_add_f32_e32 v38, 1.0, v38
	v_add_f32_e32 v39, 1.0, v39
	v_rcp_f32_e32 v38, v38
	v_rcp_f32_e32 v39, v39
	s_nop 0
	v_mul_f32_e32 v38, v36, v38
	v_mul_f32_e32 v39, v37, v39
	v_mul_f32_e32 v32, v32, v38
	v_mul_f32_e32 v33, v33, v39
	v_fmac_f32_e32 v26, v32, v32
	v_fmac_f32_e32 v26, v33, v33
	v_mul_f32_e32 v32, v32, v20
	v_mul_f32_e32 v33, v33, v21
	v_cvt_pk_bf16_f32 v43, v32, v33
	global_load_dwordx4 v[84:87], v[4:5], off
	global_load_dwordx4 v[88:91], v[6:7], off
	global_load_dwordx4 v[92:95], v[8:9], off
	v_lshl_add_u64 v[4:5], v[4:5], 0, s[28:29]
	v_lshl_add_u64 v[6:7], v[6:7], 0, s[28:29]
	v_lshl_add_u64 v[8:9], v[8:9], 0, s[34:35]
	global_store_dwordx4 v[10:11], v[40:43], off
	s_nop 1
	v_add_f32_dpp v26, v26, v26 quad_perm:[1,0,3,2] row_mask:0xf bank_mask:0xf bound_ctrl:1
	s_nop 1
	v_add_f32_dpp v26, v26, v26 quad_perm:[2,3,0,1] row_mask:0xf bank_mask:0xf bound_ctrl:1
	s_nop 1
	v_add_f32_dpp v26, v26, v26 row_half_mirror row_mask:0xf bank_mask:0xf bound_ctrl:1
	s_cmp_eq_u32 s12, 64
	s_cbranch_scc1 .Lsg_red_done_3
	s_nop 1
	v_add_f32_dpp v26, v26, v26 row_mirror row_mask:0xf bank_mask:0xf bound_ctrl:1
	v_mov_b32_e32 v31, v26
	s_nop 1
	v_permlane16_swap_b32_e32 v26, v31
	v_add_f32_e32 v26, v26, v31

.Lsg_st_done_3:
	s_or_b64 exec, exec, s[42:43]
	v_lshl_add_u64 v[10:11], v[10:11], 0, s[38:39]
	v_lshl_add_u64 v[12:13], v[12:13], 0, s[40:41]
	s_waitcnt vmcnt(29)
	v_mov_b32_e32 v26, 0
	v_lshlrev_b32_e32 v32, 16, v96
	v_and_b32_e32 v33, 0xffff0000, v96
	v_lshlrev_b32_e32 v34, 16, v100
	v_and_b32_e32 v35, 0xffff0000, v100
	v_lshlrev_b32_e32 v36, 16, v104
	v_and_b32_e32 v37, 0xffff0000, v104
	v_add_f32_e32 v32, v32, v34
	v_add_f32_e32 v33, v33, v35
	v_mul_f32_e32 v38, 0xbfb8aa3b, v36
	v_mul_f32_e32 v39, 0xbfb8aa3b, v37
	v_exp_f32_e32 v38, v38
	v_exp_f32_e32 v39, v39
	s_nop 0
	v_add_f32_e32 v38, 1.0, v38
	v_add_f32_e32 v39, 1.0, v39
	v_rcp_f32_e32 v38, v38
	v_rcp_f32_e32 v39, v39
	s_nop 0
	v_mul_f32_e32 v38, v36, v38
	v_mul_f32_e32 v39, v37, v39
	v_mul_f32_e32 v32, v32, v38
	v_mul_f32_e32 v33, v33, v39
	v_fmac_f32_e32 v26, v32, v32
	v_fmac_f32_e32 v26, v33, v33
	v_mul_f32_e32 v32, v32, v14
	v_mul_f32_e32 v33, v33, v15
	v_cvt_pk_bf16_f32 v40, v32, v33
	v_lshlrev_b32_e32 v32, 16, v97
	v_and_b32_e32 v33, 0xffff0000, v97
	v_lshlrev_b32_e32 v34, 16, v101
	v_and_b32_e32 v35, 0xffff0000, v101
	v_lshlrev_b32_e32 v36, 16, v105
	v_and_b32_e32 v37, 0xffff0000, v105
	v_add_f32_e32 v32, v32, v34
	v_add_f32_e32 v33, v33, v35
	v_mul_f32_e32 v38, 0xbfb8aa3b, v36
	v_mul_f32_e32 v39, 0xbfb8aa3b, v37
	v_exp_f32_e32 v38, v38
	v_exp_f32_e32 v39, v39
	s_nop 0
	v_add_f32_e32 v38, 1.0, v38
	v_add_f32_e32 v39, 1.0, v39
	v_rcp_f32_e32 v38, v38
	v_rcp_f32_e32 v39, v39
	s_nop 0
	v_mul_f32_e32 v38, v36, v38
	v_mul_f32_e32 v39, v37, v39
	v_mul_f32_e32 v32, v32, v38
	v_mul_f32_e32 v33, v33, v39
	v_fmac_f32_e32 v26, v32, v32
	v_fmac_f32_e32 v26, v33, v33
	v_mul_f32_e32 v32, v32, v16
	v_mul_f32_e32 v33, v33, v17
	v_cvt_pk_bf16_f32 v41, v32, v33
	v_lshlrev_b32_e32 v32, 16, v98
	v_and_b32_e32 v33, 0xffff0000, v98
	v_lshlrev_b32_e32 v34, 16, v102
	v_and_b32_e32 v35, 0xffff0000, v102
	v_lshlrev_b32_e32 v36, 16, v106
	v_and_b32_e32 v37, 0xffff0000, v106
	v_add_f32_e32 v32, v32, v34
	v_add_f32_e32 v33, v33, v35
	v_mul_f32_e32 v38, 0xbfb8aa3b, v36
	v_mul_f32_e32 v39, 0xbfb8aa3b, v37
	v_exp_f32_e32 v38, v38
	v_exp_f32_e32 v39, v39
	s_nop 0
	v_add_f32_e32 v38, 1.0, v38
	v_add_f32_e32 v39, 1.0, v39
	v_rcp_f32_e32 v38, v38
	v_rcp_f32_e32 v39, v39
	s_nop 0
	v_mul_f32_e32 v38, v36, v38
	v_mul_f32_e32 v39, v37, v39
	v_mul_f32_e32 v32, v32, v38
	v_mul_f32_e32 v33, v33, v39
	v_fmac_f32_e32 v26, v32, v32
	v_fmac_f32_e32 v26, v33, v33
	v_mul_f32_e32 v32, v32, v18
	v_mul_f32_e32 v33, v33, v19
	v_cvt_pk_bf16_f32 v42, v32, v33
	v_lshlrev_b32_e32 v32, 16, v99
	v_and_b32_e32 v33, 0xffff0000, v99
	v_lshlrev_b32_e32 v34, 16, v103
	v_and_b32_e32 v35, 0xffff0000, v103
	v_lshlrev_b32_e32 v36, 16, v107
	v_and_b32_e32 v37, 0xffff0000, v107
	v_add_f32_e32 v32, v32, v34
	v_add_f32_e32 v33, v33, v35
	v_mul_f32_e32 v38, 0xbfb8aa3b, v36
	v_mul_f32_e32 v39, 0xbfb8aa3b, v37
	v_exp_f32_e32 v38, v38
	v_exp_f32_e32 v39, v39
	s_nop 0
	v_add_f32_e32 v38, 1.0, v38
	v_add_f32_e32 v39, 1.0, v39
	v_rcp_f32_e32 v38, v38
	v_rcp_f32_e32 v39, v39
	s_nop 0
	v_mul_f32_e32 v38, v36, v38
	v_mul_f32_e32 v39, v37, v39
	v_mul_f32_e32 v32, v32, v38
	v_mul_f32_e32 v33, v33, v39
	v_fmac_f32_e32 v26, v32, v32
	v_fmac_f32_e32 v26, v33, v33
	v_mul_f32_e32 v32, v32, v20
	v_mul_f32_e32 v33, v33, v21
	v_cvt_pk_bf16_f32 v43, v32, v33
	global_load_dwordx4 v[96:99], v[4:5], off
	global_load_dwordx4 v[100:103], v[6:7], off
	global_load_dwordx4 v[104:107], v[8:9], off
	v_lshl_add_u64 v[4:5], v[4:5], 0, s[28:29]
	v_lshl_add_u64 v[6:7], v[6:7], 0, s[28:29]
	v_lshl_add_u64 v[8:9], v[8:9], 0, s[34:35]
	global_store_dwordx4 v[10:11], v[40:43], off
	s_nop 1
	v_add_f32_dpp v26, v26, v26 quad_perm:[1,0,3,2] row_mask:0xf bank_mask:0xf bound_ctrl:1
	s_nop 1
	v_add_f32_dpp v26, v26, v26 quad_perm:[2,3,0,1] row_mask:0xf bank_mask:0xf bound_ctrl:1
	s_nop 1
	v_add_f32_dpp v26, v26, v26 row_half_mirror row_mask:0xf bank_mask:0xf bound_ctrl:1
	s_cmp_eq_u32 s12, 64
	s_cbranch_scc1 .Lsg_red_done_4
	s_nop 1
	v_add_f32_dpp v26, v26, v26 row_mirror row_mask:0xf bank_mask:0xf bound_ctrl:1
	v_mov_b32_e32 v31, v26
	s_nop 1
	v_permlane16_swap_b32_e32 v26, v31
	v_add_f32_e32 v26, v26, v31

.Lsg_st_done_4:
	s_or_b64 exec, exec, s[42:43]
	v_lshl_add_u64 v[10:11], v[10:11], 0, s[38:39]
	v_lshl_add_u64 v[12:13], v[12:13], 0, s[40:41]
	s_waitcnt vmcnt(31)
	v_mov_b32_e32 v26, 0
	v_lshlrev_b32_e32 v32, 16, v108
	v_and_b32_e32 v33, 0xffff0000, v108
	v_lshlrev_b32_e32 v34, 16, v112
	v_and_b32_e32 v35, 0xffff0000, v112
	v_lshlrev_b32_e32 v36, 16, v116
	v_and_b32_e32 v37, 0xffff0000, v116
	v_add_f32_e32 v32, v32, v34
	v_add_f32_e32 v33, v33, v35
	v_mul_f32_e32 v38, 0xbfb8aa3b, v36
	v_mul_f32_e32 v39, 0xbfb8aa3b, v37
	v_exp_f32_e32 v38, v38
	v_exp_f32_e32 v39, v39
	s_nop 0
	v_add_f32_e32 v38, 1.0, v38
	v_add_f32_e32 v39, 1.0, v39
	v_rcp_f32_e32 v38, v38
	v_rcp_f32_e32 v39, v39
	s_nop 0
	v_mul_f32_e32 v38, v36, v38
	v_mul_f32_e32 v39, v37, v39
	v_mul_f32_e32 v32, v32, v38
	v_mul_f32_e32 v33, v33, v39
	v_fmac_f32_e32 v26, v32, v32
	v_fmac_f32_e32 v26, v33, v33
	v_mul_f32_e32 v32, v32, v14
	v_mul_f32_e32 v33, v33, v15
	v_cvt_pk_bf16_f32 v40, v32, v33
	v_lshlrev_b32_e32 v32, 16, v109
	v_and_b32_e32 v33, 0xffff0000, v109
	v_lshlrev_b32_e32 v34, 16, v113
	v_and_b32_e32 v35, 0xffff0000, v113
	v_lshlrev_b32_e32 v36, 16, v117
	v_and_b32_e32 v37, 0xffff0000, v117
	v_add_f32_e32 v32, v32, v34
	v_add_f32_e32 v33, v33, v35
	v_mul_f32_e32 v38, 0xbfb8aa3b, v36
	v_mul_f32_e32 v39, 0xbfb8aa3b, v37
	v_exp_f32_e32 v38, v38
	v_exp_f32_e32 v39, v39
	s_nop 0
	v_add_f32_e32 v38, 1.0, v38
	v_add_f32_e32 v39, 1.0, v39
	v_rcp_f32_e32 v38, v38
	v_rcp_f32_e32 v39, v39
	s_nop 0
	v_mul_f32_e32 v38, v36, v38
	v_mul_f32_e32 v39, v37, v39
	v_mul_f32_e32 v32, v32, v38
	v_mul_f32_e32 v33, v33, v39
	v_fmac_f32_e32 v26, v32, v32
	v_fmac_f32_e32 v26, v33, v33
	v_mul_f32_e32 v32, v32, v16
	v_mul_f32_e32 v33, v33, v17
	v_cvt_pk_bf16_f32 v41, v32, v33
	v_lshlrev_b32_e32 v32, 16, v110
	v_and_b32_e32 v33, 0xffff0000, v110
	v_lshlrev_b32_e32 v34, 16, v114
	v_and_b32_e32 v35, 0xffff0000, v114
	v_lshlrev_b32_e32 v36, 16, v118
	v_and_b32_e32 v37, 0xffff0000, v118
	v_add_f32_e32 v32, v32, v34
	v_add_f32_e32 v33, v33, v35
	v_mul_f32_e32 v38, 0xbfb8aa3b, v36
	v_mul_f32_e32 v39, 0xbfb8aa3b, v37
	v_exp_f32_e32 v38, v38
	v_exp_f32_e32 v39, v39
	s_nop 0
	v_add_f32_e32 v38, 1.0, v38
	v_add_f32_e32 v39, 1.0, v39
	v_rcp_f32_e32 v38, v38
	v_rcp_f32_e32 v39, v39
	s_nop 0
	v_mul_f32_e32 v38, v36, v38
	v_mul_f32_e32 v39, v37, v39
	v_mul_f32_e32 v32, v32, v38
	v_mul_f32_e32 v33, v33, v39
	v_fmac_f32_e32 v26, v32, v32
	v_fmac_f32_e32 v26, v33, v33
	v_mul_f32_e32 v32, v32, v18
	v_mul_f32_e32 v33, v33, v19
	v_cvt_pk_bf16_f32 v42, v32, v33
	v_lshlrev_b32_e32 v32, 16, v111
	v_and_b32_e32 v33, 0xffff0000, v111
	v_lshlrev_b32_e32 v34, 16, v115
	v_and_b32_e32 v35, 0xffff0000, v115
	v_lshlrev_b32_e32 v36, 16, v119
	v_and_b32_e32 v37, 0xffff0000, v119
	v_add_f32_e32 v32, v32, v34
	v_add_f32_e32 v33, v33, v35
	v_mul_f32_e32 v38, 0xbfb8aa3b, v36
	v_mul_f32_e32 v39, 0xbfb8aa3b, v37
	v_exp_f32_e32 v38, v38
	v_exp_f32_e32 v39, v39
	s_nop 0
	v_add_f32_e32 v38, 1.0, v38
	v_add_f32_e32 v39, 1.0, v39
	v_rcp_f32_e32 v38, v38
	v_rcp_f32_e32 v39, v39
	s_nop 0
	v_mul_f32_e32 v38, v36, v38
	v_mul_f32_e32 v39, v37, v39
	v_mul_f32_e32 v32, v32, v38
	v_mul_f32_e32 v33, v33, v39
	v_fmac_f32_e32 v26, v32, v32
	v_fmac_f32_e32 v26, v33, v33
	v_mul_f32_e32 v32, v32, v20
	v_mul_f32_e32 v33, v33, v21
	v_cvt_pk_bf16_f32 v43, v32, v33
	global_load_dwordx4 v[108:111], v[4:5], off
	global_load_dwordx4 v[112:115], v[6:7], off
	global_load_dwordx4 v[116:119], v[8:9], off
	v_lshl_add_u64 v[4:5], v[4:5], 0, s[28:29]
	v_lshl_add_u64 v[6:7], v[6:7], 0, s[28:29]
	v_lshl_add_u64 v[8:9], v[8:9], 0, s[34:35]
	global_store_dwordx4 v[10:11], v[40:43], off
	s_nop 1
	v_add_f32_dpp v26, v26, v26 quad_perm:[1,0,3,2] row_mask:0xf bank_mask:0xf bound_ctrl:1
	s_nop 1
	v_add_f32_dpp v26, v26, v26 quad_perm:[2,3,0,1] row_mask:0xf bank_mask:0xf bound_ctrl:1
	s_nop 1
	v_add_f32_dpp v26, v26, v26 row_half_mirror row_mask:0xf bank_mask:0xf bound_ctrl:1
	s_cmp_eq_u32 s12, 64
	s_cbranch_scc1 .Lsg_red_done_5
	s_nop 1
	v_add_f32_dpp v26, v26, v26 row_mirror row_mask:0xf bank_mask:0xf bound_ctrl:1
	v_mov_b32_e32 v31, v26
	s_nop 1
	v_permlane16_swap_b32_e32 v26, v31
	v_add_f32_e32 v26, v26, v31

.Lsg_st_done_5:
	s_or_b64 exec, exec, s[42:43]
	v_lshl_add_u64 v[10:11], v[10:11], 0, s[38:39]
	v_lshl_add_u64 v[12:13], v[12:13], 0, s[40:41]
	s_waitcnt vmcnt(33)
	v_mov_b32_e32 v26, 0
	v_lshlrev_b32_e32 v32, 16, v120
	v_and_b32_e32 v33, 0xffff0000, v120
	v_lshlrev_b32_e32 v34, 16, v124
	v_and_b32_e32 v35, 0xffff0000, v124
	v_lshlrev_b32_e32 v36, 16, v128
	v_and_b32_e32 v37, 0xffff0000, v128
	v_add_f32_e32 v32, v32, v34
	v_add_f32_e32 v33, v33, v35
	v_mul_f32_e32 v38, 0xbfb8aa3b, v36
	v_mul_f32_e32 v39, 0xbfb8aa3b, v37
	v_exp_f32_e32 v38, v38
	v_exp_f32_e32 v39, v39
	s_nop 0
	v_add_f32_e32 v38, 1.0, v38
	v_add_f32_e32 v39, 1.0, v39
	v_rcp_f32_e32 v38, v38
	v_rcp_f32_e32 v39, v39
	s_nop 0
	v_mul_f32_e32 v38, v36, v38
	v_mul_f32_e32 v39, v37, v39
	v_mul_f32_e32 v32, v32, v38
	v_mul_f32_e32 v33, v33, v39
	v_fmac_f32_e32 v26, v32, v32
	v_fmac_f32_e32 v26, v33, v33
	v_mul_f32_e32 v32, v32, v14
	v_mul_f32_e32 v33, v33, v15
	v_cvt_pk_bf16_f32 v40, v32, v33
	v_lshlrev_b32_e32 v32, 16, v121
	v_and_b32_e32 v33, 0xffff0000, v121
	v_lshlrev_b32_e32 v34, 16, v125
	v_and_b32_e32 v35, 0xffff0000, v125
	v_lshlrev_b32_e32 v36, 16, v129
	v_and_b32_e32 v37, 0xffff0000, v129
	v_add_f32_e32 v32, v32, v34
	v_add_f32_e32 v33, v33, v35
	v_mul_f32_e32 v38, 0xbfb8aa3b, v36
	v_mul_f32_e32 v39, 0xbfb8aa3b, v37
	v_exp_f32_e32 v38, v38
	v_exp_f32_e32 v39, v39
	s_nop 0
	v_add_f32_e32 v38, 1.0, v38
	v_add_f32_e32 v39, 1.0, v39
	v_rcp_f32_e32 v38, v38
	v_rcp_f32_e32 v39, v39
	s_nop 0
	v_mul_f32_e32 v38, v36, v38
	v_mul_f32_e32 v39, v37, v39
	v_mul_f32_e32 v32, v32, v38
	v_mul_f32_e32 v33, v33, v39
	v_fmac_f32_e32 v26, v32, v32
	v_fmac_f32_e32 v26, v33, v33
	v_mul_f32_e32 v32, v32, v16
	v_mul_f32_e32 v33, v33, v17
	v_cvt_pk_bf16_f32 v41, v32, v33
	v_lshlrev_b32_e32 v32, 16, v122
	v_and_b32_e32 v33, 0xffff0000, v122
	v_lshlrev_b32_e32 v34, 16, v126
	v_and_b32_e32 v35, 0xffff0000, v126
	v_lshlrev_b32_e32 v36, 16, v130
	v_and_b32_e32 v37, 0xffff0000, v130
	v_add_f32_e32 v32, v32, v34
	v_add_f32_e32 v33, v33, v35
	v_mul_f32_e32 v38, 0xbfb8aa3b, v36
	v_mul_f32_e32 v39, 0xbfb8aa3b, v37
	v_exp_f32_e32 v38, v38
	v_exp_f32_e32 v39, v39
	s_nop 0
	v_add_f32_e32 v38, 1.0, v38
	v_add_f32_e32 v39, 1.0, v39
	v_rcp_f32_e32 v38, v38
	v_rcp_f32_e32 v39, v39
	s_nop 0
	v_mul_f32_e32 v38, v36, v38
	v_mul_f32_e32 v39, v37, v39
	v_mul_f32_e32 v32, v32, v38
	v_mul_f32_e32 v33, v33, v39
	v_fmac_f32_e32 v26, v32, v32
	v_fmac_f32_e32 v26, v33, v33
	v_mul_f32_e32 v32, v32, v18
	v_mul_f32_e32 v33, v33, v19
	v_cvt_pk_bf16_f32 v42, v32, v33
	v_lshlrev_b32_e32 v32, 16, v123
	v_and_b32_e32 v33, 0xffff0000, v123
	v_lshlrev_b32_e32 v34, 16, v127
	v_and_b32_e32 v35, 0xffff0000, v127
	v_lshlrev_b32_e32 v36, 16, v131
	v_and_b32_e32 v37, 0xffff0000, v131
	v_add_f32_e32 v32, v32, v34
	v_add_f32_e32 v33, v33, v35
	v_mul_f32_e32 v38, 0xbfb8aa3b, v36
	v_mul_f32_e32 v39, 0xbfb8aa3b, v37
	v_exp_f32_e32 v38, v38
	v_exp_f32_e32 v39, v39
	s_nop 0
	v_add_f32_e32 v38, 1.0, v38
	v_add_f32_e32 v39, 1.0, v39
	v_rcp_f32_e32 v38, v38
	v_rcp_f32_e32 v39, v39
	s_nop 0
	v_mul_f32_e32 v38, v36, v38
	v_mul_f32_e32 v39, v37, v39
	v_mul_f32_e32 v32, v32, v38
	v_mul_f32_e32 v33, v33, v39
	v_fmac_f32_e32 v26, v32, v32
	v_fmac_f32_e32 v26, v33, v33
	v_mul_f32_e32 v32, v32, v20
	v_mul_f32_e32 v33, v33, v21
	v_cvt_pk_bf16_f32 v43, v32, v33
	global_load_dwordx4 v[120:123], v[4:5], off
	global_load_dwordx4 v[124:127], v[6:7], off
	global_load_dwordx4 v[128:131], v[8:9], off
	v_lshl_add_u64 v[4:5], v[4:5], 0, s[28:29]
	v_lshl_add_u64 v[6:7], v[6:7], 0, s[28:29]
	v_lshl_add_u64 v[8:9], v[8:9], 0, s[34:35]
	global_store_dwordx4 v[10:11], v[40:43], off
	s_nop 1
	v_add_f32_dpp v26, v26, v26 quad_perm:[1,0,3,2] row_mask:0xf bank_mask:0xf bound_ctrl:1
	s_nop 1
	v_add_f32_dpp v26, v26, v26 quad_perm:[2,3,0,1] row_mask:0xf bank_mask:0xf bound_ctrl:1
	s_nop 1
	v_add_f32_dpp v26, v26, v26 row_half_mirror row_mask:0xf bank_mask:0xf bound_ctrl:1
	s_cmp_eq_u32 s12, 64
	s_cbranch_scc1 .Lsg_red_done_6
	s_nop 1
	v_add_f32_dpp v26, v26, v26 row_mirror row_mask:0xf bank_mask:0xf bound_ctrl:1
	v_mov_b32_e32 v31, v26
	s_nop 1
	v_permlane16_swap_b32_e32 v26, v31
	v_add_f32_e32 v26, v26, v31

.Lsg_st_done_6:
	s_or_b64 exec, exec, s[42:43]
	v_lshl_add_u64 v[10:11], v[10:11], 0, s[38:39]
	v_lshl_add_u64 v[12:13], v[12:13], 0, s[40:41]
	s_waitcnt vmcnt(35)
	v_mov_b32_e32 v26, 0
	v_lshlrev_b32_e32 v32, 16, v132
	v_and_b32_e32 v33, 0xffff0000, v132
	v_lshlrev_b32_e32 v34, 16, v136
	v_and_b32_e32 v35, 0xffff0000, v136
	v_lshlrev_b32_e32 v36, 16, v140
	v_and_b32_e32 v37, 0xffff0000, v140
	v_add_f32_e32 v32, v32, v34
	v_add_f32_e32 v33, v33, v35
	v_mul_f32_e32 v38, 0xbfb8aa3b, v36
	v_mul_f32_e32 v39, 0xbfb8aa3b, v37
	v_exp_f32_e32 v38, v38
	v_exp_f32_e32 v39, v39
	s_nop 0
	v_add_f32_e32 v38, 1.0, v38
	v_add_f32_e32 v39, 1.0, v39
	v_rcp_f32_e32 v38, v38
	v_rcp_f32_e32 v39, v39
	s_nop 0
	v_mul_f32_e32 v38, v36, v38
	v_mul_f32_e32 v39, v37, v39
	v_mul_f32_e32 v32, v32, v38
	v_mul_f32_e32 v33, v33, v39
	v_fmac_f32_e32 v26, v32, v32
	v_fmac_f32_e32 v26, v33, v33
	v_mul_f32_e32 v32, v32, v14
	v_mul_f32_e32 v33, v33, v15
	v_cvt_pk_bf16_f32 v40, v32, v33
	v_lshlrev_b32_e32 v32, 16, v133
	v_and_b32_e32 v33, 0xffff0000, v133
	v_lshlrev_b32_e32 v34, 16, v137
	v_and_b32_e32 v35, 0xffff0000, v137
	v_lshlrev_b32_e32 v36, 16, v141
	v_and_b32_e32 v37, 0xffff0000, v141
	v_add_f32_e32 v32, v32, v34
	v_add_f32_e32 v33, v33, v35
	v_mul_f32_e32 v38, 0xbfb8aa3b, v36
	v_mul_f32_e32 v39, 0xbfb8aa3b, v37
	v_exp_f32_e32 v38, v38
	v_exp_f32_e32 v39, v39
	s_nop 0
	v_add_f32_e32 v38, 1.0, v38
	v_add_f32_e32 v39, 1.0, v39
	v_rcp_f32_e32 v38, v38
	v_rcp_f32_e32 v39, v39
	s_nop 0
	v_mul_f32_e32 v38, v36, v38
	v_mul_f32_e32 v39, v37, v39
	v_mul_f32_e32 v32, v32, v38
	v_mul_f32_e32 v33, v33, v39
	v_fmac_f32_e32 v26, v32, v32
	v_fmac_f32_e32 v26, v33, v33
	v_mul_f32_e32 v32, v32, v16
	v_mul_f32_e32 v33, v33, v17
	v_cvt_pk_bf16_f32 v41, v32, v33
	v_lshlrev_b32_e32 v32, 16, v134
	v_and_b32_e32 v33, 0xffff0000, v134
	v_lshlrev_b32_e32 v34, 16, v138
	v_and_b32_e32 v35, 0xffff0000, v138
	v_lshlrev_b32_e32 v36, 16, v142
	v_and_b32_e32 v37, 0xffff0000, v142
	v_add_f32_e32 v32, v32, v34
	v_add_f32_e32 v33, v33, v35
	v_mul_f32_e32 v38, 0xbfb8aa3b, v36
	v_mul_f32_e32 v39, 0xbfb8aa3b, v37
	v_exp_f32_e32 v38, v38
	v_exp_f32_e32 v39, v39
	s_nop 0
	v_add_f32_e32 v38, 1.0, v38
	v_add_f32_e32 v39, 1.0, v39
	v_rcp_f32_e32 v38, v38
	v_rcp_f32_e32 v39, v39
	s_nop 0
	v_mul_f32_e32 v38, v36, v38
	v_mul_f32_e32 v39, v37, v39
	v_mul_f32_e32 v32, v32, v38
	v_mul_f32_e32 v33, v33, v39
	v_fmac_f32_e32 v26, v32, v32
	v_fmac_f32_e32 v26, v33, v33
	v_mul_f32_e32 v32, v32, v18
	v_mul_f32_e32 v33, v33, v19
	v_cvt_pk_bf16_f32 v42, v32, v33
	v_lshlrev_b32_e32 v32, 16, v135
	v_and_b32_e32 v33, 0xffff0000, v135
	v_lshlrev_b32_e32 v34, 16, v139
	v_and_b32_e32 v35, 0xffff0000, v139
	v_lshlrev_b32_e32 v36, 16, v143
	v_and_b32_e32 v37, 0xffff0000, v143
	v_add_f32_e32 v32, v32, v34
	v_add_f32_e32 v33, v33, v35
	v_mul_f32_e32 v38, 0xbfb8aa3b, v36
	v_mul_f32_e32 v39, 0xbfb8aa3b, v37
	v_exp_f32_e32 v38, v38
	v_exp_f32_e32 v39, v39
	s_nop 0
	v_add_f32_e32 v38, 1.0, v38
	v_add_f32_e32 v39, 1.0, v39
	v_rcp_f32_e32 v38, v38
	v_rcp_f32_e32 v39, v39
	s_nop 0
	v_mul_f32_e32 v38, v36, v38
	v_mul_f32_e32 v39, v37, v39
	v_mul_f32_e32 v32, v32, v38
	v_mul_f32_e32 v33, v33, v39
	v_fmac_f32_e32 v26, v32, v32
	v_fmac_f32_e32 v26, v33, v33
	v_mul_f32_e32 v32, v32, v20
	v_mul_f32_e32 v33, v33, v21
	v_cvt_pk_bf16_f32 v43, v32, v33
	global_load_dwordx4 v[132:135], v[4:5], off
	global_load_dwordx4 v[136:139], v[6:7], off
	global_load_dwordx4 v[140:143], v[8:9], off
	v_lshl_add_u64 v[4:5], v[4:5], 0, s[28:29]
	v_lshl_add_u64 v[6:7], v[6:7], 0, s[28:29]
	v_lshl_add_u64 v[8:9], v[8:9], 0, s[34:35]
	global_store_dwordx4 v[10:11], v[40:43], off
	s_nop 1
	v_add_f32_dpp v26, v26, v26 quad_perm:[1,0,3,2] row_mask:0xf bank_mask:0xf bound_ctrl:1
	s_nop 1
	v_add_f32_dpp v26, v26, v26 quad_perm:[2,3,0,1] row_mask:0xf bank_mask:0xf bound_ctrl:1
	s_nop 1
	v_add_f32_dpp v26, v26, v26 row_half_mirror row_mask:0xf bank_mask:0xf bound_ctrl:1
	s_cmp_eq_u32 s12, 64
	s_cbranch_scc1 .Lsg_red_done_7
	s_nop 1
	v_add_f32_dpp v26, v26, v26 row_mirror row_mask:0xf bank_mask:0xf bound_ctrl:1
	v_mov_b32_e32 v31, v26
	s_nop 1
	v_permlane16_swap_b32_e32 v26, v31
	v_add_f32_e32 v26, v26, v31

.Lsg_st_done_7:
	s_or_b64 exec, exec, s[42:43]
	v_lshl_add_u64 v[10:11], v[10:11], 0, s[38:39]
	v_lshl_add_u64 v[12:13], v[12:13], 0, s[40:41]
	s_waitcnt vmcnt(37)
	v_mov_b32_e32 v26, 0
	v_lshlrev_b32_e32 v32, 16, v48
	v_and_b32_e32 v33, 0xffff0000, v48
	v_lshlrev_b32_e32 v34, 16, v52
	v_and_b32_e32 v35, 0xffff0000, v52
	v_lshlrev_b32_e32 v36, 16, v56
	v_and_b32_e32 v37, 0xffff0000, v56
	v_add_f32_e32 v32, v32, v34
	v_add_f32_e32 v33, v33, v35
	v_mul_f32_e32 v38, 0xbfb8aa3b, v36
	v_mul_f32_e32 v39, 0xbfb8aa3b, v37
	v_exp_f32_e32 v38, v38
	v_exp_f32_e32 v39, v39
	s_nop 0
	v_add_f32_e32 v38, 1.0, v38
	v_add_f32_e32 v39, 1.0, v39
	v_rcp_f32_e32 v38, v38
	v_rcp_f32_e32 v39, v39
	s_nop 0
	v_mul_f32_e32 v38, v36, v38
	v_mul_f32_e32 v39, v37, v39
	v_mul_f32_e32 v32, v32, v38
	v_mul_f32_e32 v33, v33, v39
	v_fmac_f32_e32 v26, v32, v32
	v_fmac_f32_e32 v26, v33, v33
	v_mul_f32_e32 v32, v32, v14
	v_mul_f32_e32 v33, v33, v15
	v_cvt_pk_bf16_f32 v40, v32, v33
	v_lshlrev_b32_e32 v32, 16, v49
	v_and_b32_e32 v33, 0xffff0000, v49
	v_lshlrev_b32_e32 v34, 16, v53
	v_and_b32_e32 v35, 0xffff0000, v53
	v_lshlrev_b32_e32 v36, 16, v57
	v_and_b32_e32 v37, 0xffff0000, v57
	v_add_f32_e32 v32, v32, v34
	v_add_f32_e32 v33, v33, v35
	v_mul_f32_e32 v38, 0xbfb8aa3b, v36
	v_mul_f32_e32 v39, 0xbfb8aa3b, v37
	v_exp_f32_e32 v38, v38
	v_exp_f32_e32 v39, v39
	s_nop 0
	v_add_f32_e32 v38, 1.0, v38
	v_add_f32_e32 v39, 1.0, v39
	v_rcp_f32_e32 v38, v38
	v_rcp_f32_e32 v39, v39
	s_nop 0
	v_mul_f32_e32 v38, v36, v38
	v_mul_f32_e32 v39, v37, v39
	v_mul_f32_e32 v32, v32, v38
	v_mul_f32_e32 v33, v33, v39
	v_fmac_f32_e32 v26, v32, v32
	v_fmac_f32_e32 v26, v33, v33
	v_mul_f32_e32 v32, v32, v16
	v_mul_f32_e32 v33, v33, v17
	v_cvt_pk_bf16_f32 v41, v32, v33
	v_lshlrev_b32_e32 v32, 16, v50
	v_and_b32_e32 v33, 0xffff0000, v50
	v_lshlrev_b32_e32 v34, 16, v54
	v_and_b32_e32 v35, 0xffff0000, v54
	v_lshlrev_b32_e32 v36, 16, v58
	v_and_b32_e32 v37, 0xffff0000, v58
	v_add_f32_e32 v32, v32, v34
	v_add_f32_e32 v33, v33, v35
	v_mul_f32_e32 v38, 0xbfb8aa3b, v36
	v_mul_f32_e32 v39, 0xbfb8aa3b, v37
	v_exp_f32_e32 v38, v38
	v_exp_f32_e32 v39, v39
	s_nop 0
	v_add_f32_e32 v38, 1.0, v38
	v_add_f32_e32 v39, 1.0, v39
	v_rcp_f32_e32 v38, v38
	v_rcp_f32_e32 v39, v39
	s_nop 0
	v_mul_f32_e32 v38, v36, v38
	v_mul_f32_e32 v39, v37, v39
	v_mul_f32_e32 v32, v32, v38
	v_mul_f32_e32 v33, v33, v39
	v_fmac_f32_e32 v26, v32, v32
	v_fmac_f32_e32 v26, v33, v33
	v_mul_f32_e32 v32, v32, v18
	v_mul_f32_e32 v33, v33, v19
	v_cvt_pk_bf16_f32 v42, v32, v33
	v_lshlrev_b32_e32 v32, 16, v51
	v_and_b32_e32 v33, 0xffff0000, v51
	v_lshlrev_b32_e32 v34, 16, v55
	v_and_b32_e32 v35, 0xffff0000, v55
	v_lshlrev_b32_e32 v36, 16, v59
	v_and_b32_e32 v37, 0xffff0000, v59
	v_add_f32_e32 v32, v32, v34
	v_add_f32_e32 v33, v33, v35
	v_mul_f32_e32 v38, 0xbfb8aa3b, v36
	v_mul_f32_e32 v39, 0xbfb8aa3b, v37
	v_exp_f32_e32 v38, v38
	v_exp_f32_e32 v39, v39
	s_nop 0
	v_add_f32_e32 v38, 1.0, v38
	v_add_f32_e32 v39, 1.0, v39
	v_rcp_f32_e32 v38, v38
	v_rcp_f32_e32 v39, v39
	s_nop 0
	v_mul_f32_e32 v38, v36, v38
	v_mul_f32_e32 v39, v37, v39
	v_mul_f32_e32 v32, v32, v38
	v_mul_f32_e32 v33, v33, v39
	v_fmac_f32_e32 v26, v32, v32
	v_fmac_f32_e32 v26, v33, v33
	v_mul_f32_e32 v32, v32, v20
	v_mul_f32_e32 v33, v33, v21
	v_cvt_pk_bf16_f32 v43, v32, v33
	global_store_dwordx4 v[10:11], v[40:43], off
	s_nop 1
	v_add_f32_dpp v26, v26, v26 quad_perm:[1,0,3,2] row_mask:0xf bank_mask:0xf bound_ctrl:1
	s_nop 1
	v_add_f32_dpp v26, v26, v26 quad_perm:[2,3,0,1] row_mask:0xf bank_mask:0xf bound_ctrl:1
	s_nop 1
	v_add_f32_dpp v26, v26, v26 row_half_mirror row_mask:0xf bank_mask:0xf bound_ctrl:1
	s_cmp_eq_u32 s12, 64
	s_cbranch_scc1 .Lsg_red_done_8
	s_nop 1
	v_add_f32_dpp v26, v26, v26 row_mirror row_mask:0xf bank_mask:0xf bound_ctrl:1
	v_mov_b32_e32 v31, v26
	s_nop 1
	v_permlane16_swap_b32_e32 v26, v31
	v_add_f32_e32 v26, v26, v31

.Lsg_st_done_8:
	s_or_b64 exec, exec, s[42:43]
	v_lshl_add_u64 v[10:11], v[10:11], 0, s[38:39]
	v_lshl_add_u64 v[12:13], v[12:13], 0, s[40:41]
	s_waitcnt vmcnt(34)
	v_mov_b32_e32 v26, 0
	v_lshlrev_b32_e32 v32, 16, v60
	v_and_b32_e32 v33, 0xffff0000, v60
	v_lshlrev_b32_e32 v34, 16, v64
	v_and_b32_e32 v35, 0xffff0000, v64
	v_lshlrev_b32_e32 v36, 16, v68
	v_and_b32_e32 v37, 0xffff0000, v68
	v_add_f32_e32 v32, v32, v34
	v_add_f32_e32 v33, v33, v35
	v_mul_f32_e32 v38, 0xbfb8aa3b, v36
	v_mul_f32_e32 v39, 0xbfb8aa3b, v37
	v_exp_f32_e32 v38, v38
	v_exp_f32_e32 v39, v39
	s_nop 0
	v_add_f32_e32 v38, 1.0, v38
	v_add_f32_e32 v39, 1.0, v39
	v_rcp_f32_e32 v38, v38
	v_rcp_f32_e32 v39, v39
	s_nop 0
	v_mul_f32_e32 v38, v36, v38
	v_mul_f32_e32 v39, v37, v39
	v_mul_f32_e32 v32, v32, v38
	v_mul_f32_e32 v33, v33, v39
	v_fmac_f32_e32 v26, v32, v32
	v_fmac_f32_e32 v26, v33, v33
	v_mul_f32_e32 v32, v32, v14
	v_mul_f32_e32 v33, v33, v15
	v_cvt_pk_bf16_f32 v40, v32, v33
	v_lshlrev_b32_e32 v32, 16, v61
	v_and_b32_e32 v33, 0xffff0000, v61
	v_lshlrev_b32_e32 v34, 16, v65
	v_and_b32_e32 v35, 0xffff0000, v65
	v_lshlrev_b32_e32 v36, 16, v69
	v_and_b32_e32 v37, 0xffff0000, v69
	v_add_f32_e32 v32, v32, v34
	v_add_f32_e32 v33, v33, v35
	v_mul_f32_e32 v38, 0xbfb8aa3b, v36
	v_mul_f32_e32 v39, 0xbfb8aa3b, v37
	v_exp_f32_e32 v38, v38
	v_exp_f32_e32 v39, v39
	s_nop 0
	v_add_f32_e32 v38, 1.0, v38
	v_add_f32_e32 v39, 1.0, v39
	v_rcp_f32_e32 v38, v38
	v_rcp_f32_e32 v39, v39
	s_nop 0
	v_mul_f32_e32 v38, v36, v38
	v_mul_f32_e32 v39, v37, v39
	v_mul_f32_e32 v32, v32, v38
	v_mul_f32_e32 v33, v33, v39
	v_fmac_f32_e32 v26, v32, v32
	v_fmac_f32_e32 v26, v33, v33
	v_mul_f32_e32 v32, v32, v16
	v_mul_f32_e32 v33, v33, v17
	v_cvt_pk_bf16_f32 v41, v32, v33
	v_lshlrev_b32_e32 v32, 16, v62
	v_and_b32_e32 v33, 0xffff0000, v62
	v_lshlrev_b32_e32 v34, 16, v66
	v_and_b32_e32 v35, 0xffff0000, v66
	v_lshlrev_b32_e32 v36, 16, v70
	v_and_b32_e32 v37, 0xffff0000, v70
	v_add_f32_e32 v32, v32, v34
	v_add_f32_e32 v33, v33, v35
	v_mul_f32_e32 v38, 0xbfb8aa3b, v36
	v_mul_f32_e32 v39, 0xbfb8aa3b, v37
	v_exp_f32_e32 v38, v38
	v_exp_f32_e32 v39, v39
	s_nop 0
	v_add_f32_e32 v38, 1.0, v38
	v_add_f32_e32 v39, 1.0, v39
	v_rcp_f32_e32 v38, v38
	v_rcp_f32_e32 v39, v39
	s_nop 0
	v_mul_f32_e32 v38, v36, v38
	v_mul_f32_e32 v39, v37, v39
	v_mul_f32_e32 v32, v32, v38
	v_mul_f32_e32 v33, v33, v39
	v_fmac_f32_e32 v26, v32, v32
	v_fmac_f32_e32 v26, v33, v33
	v_mul_f32_e32 v32, v32, v18
	v_mul_f32_e32 v33, v33, v19
	v_cvt_pk_bf16_f32 v42, v32, v33
	v_lshlrev_b32_e32 v32, 16, v63
	v_and_b32_e32 v33, 0xffff0000, v63
	v_lshlrev_b32_e32 v34, 16, v67
	v_and_b32_e32 v35, 0xffff0000, v67
	v_lshlrev_b32_e32 v36, 16, v71
	v_and_b32_e32 v37, 0xffff0000, v71
	v_add_f32_e32 v32, v32, v34
	v_add_f32_e32 v33, v33, v35
	v_mul_f32_e32 v38, 0xbfb8aa3b, v36
	v_mul_f32_e32 v39, 0xbfb8aa3b, v37
	v_exp_f32_e32 v38, v38
	v_exp_f32_e32 v39, v39
	s_nop 0
	v_add_f32_e32 v38, 1.0, v38
	v_add_f32_e32 v39, 1.0, v39
	v_rcp_f32_e32 v38, v38
	v_rcp_f32_e32 v39, v39
	s_nop 0
	v_mul_f32_e32 v38, v36, v38
	v_mul_f32_e32 v39, v37, v39
	v_mul_f32_e32 v32, v32, v38
	v_mul_f32_e32 v33, v33, v39
	v_fmac_f32_e32 v26, v32, v32
	v_fmac_f32_e32 v26, v33, v33
	v_mul_f32_e32 v32, v32, v20
	v_mul_f32_e32 v33, v33, v21
	v_cvt_pk_bf16_f32 v43, v32, v33
	global_store_dwordx4 v[10:11], v[40:43], off
	s_nop 1
	v_add_f32_dpp v26, v26, v26 quad_perm:[1,0,3,2] row_mask:0xf bank_mask:0xf bound_ctrl:1
	s_nop 1
	v_add_f32_dpp v26, v26, v26 quad_perm:[2,3,0,1] row_mask:0xf bank_mask:0xf bound_ctrl:1
	s_nop 1
	v_add_f32_dpp v26, v26, v26 row_half_mirror row_mask:0xf bank_mask:0xf bound_ctrl:1
	s_cmp_eq_u32 s12, 64
	s_cbranch_scc1 .Lsg_red_done_9
	s_nop 1
	v_add_f32_dpp v26, v26, v26 row_mirror row_mask:0xf bank_mask:0xf bound_ctrl:1
	v_mov_b32_e32 v31, v26
	s_nop 1
	v_permlane16_swap_b32_e32 v26, v31
	v_add_f32_e32 v26, v26, v31

.Lsg_st_done_9:
	s_or_b64 exec, exec, s[42:43]
	v_lshl_add_u64 v[10:11], v[10:11], 0, s[38:39]
	v_lshl_add_u64 v[12:13], v[12:13], 0, s[40:41]
	s_waitcnt vmcnt(31)
	v_mov_b32_e32 v26, 0
	v_lshlrev_b32_e32 v32, 16, v72
	v_and_b32_e32 v33, 0xffff0000, v72
	v_lshlrev_b32_e32 v34, 16, v76
	v_and_b32_e32 v35, 0xffff0000, v76
	v_lshlrev_b32_e32 v36, 16, v80
	v_and_b32_e32 v37, 0xffff0000, v80
	v_add_f32_e32 v32, v32, v34
	v_add_f32_e32 v33, v33, v35
	v_mul_f32_e32 v38, 0xbfb8aa3b, v36
	v_mul_f32_e32 v39, 0xbfb8aa3b, v37
	v_exp_f32_e32 v38, v38
	v_exp_f32_e32 v39, v39
	s_nop 0
	v_add_f32_e32 v38, 1.0, v38
	v_add_f32_e32 v39, 1.0, v39
	v_rcp_f32_e32 v38, v38
	v_rcp_f32_e32 v39, v39
	s_nop 0
	v_mul_f32_e32 v38, v36, v38
	v_mul_f32_e32 v39, v37, v39
	v_mul_f32_e32 v32, v32, v38
	v_mul_f32_e32 v33, v33, v39
	v_fmac_f32_e32 v26, v32, v32
	v_fmac_f32_e32 v26, v33, v33
	v_mul_f32_e32 v32, v32, v14
	v_mul_f32_e32 v33, v33, v15
	v_cvt_pk_bf16_f32 v40, v32, v33
	v_lshlrev_b32_e32 v32, 16, v73
	v_and_b32_e32 v33, 0xffff0000, v73
	v_lshlrev_b32_e32 v34, 16, v77
	v_and_b32_e32 v35, 0xffff0000, v77
	v_lshlrev_b32_e32 v36, 16, v81
	v_and_b32_e32 v37, 0xffff0000, v81
	v_add_f32_e32 v32, v32, v34
	v_add_f32_e32 v33, v33, v35
	v_mul_f32_e32 v38, 0xbfb8aa3b, v36
	v_mul_f32_e32 v39, 0xbfb8aa3b, v37
	v_exp_f32_e32 v38, v38
	v_exp_f32_e32 v39, v39
	s_nop 0
	v_add_f32_e32 v38, 1.0, v38
	v_add_f32_e32 v39, 1.0, v39
	v_rcp_f32_e32 v38, v38
	v_rcp_f32_e32 v39, v39
	s_nop 0
	v_mul_f32_e32 v38, v36, v38
	v_mul_f32_e32 v39, v37, v39
	v_mul_f32_e32 v32, v32, v38
	v_mul_f32_e32 v33, v33, v39
	v_fmac_f32_e32 v26, v32, v32
	v_fmac_f32_e32 v26, v33, v33
	v_mul_f32_e32 v32, v32, v16
	v_mul_f32_e32 v33, v33, v17
	v_cvt_pk_bf16_f32 v41, v32, v33
	v_lshlrev_b32_e32 v32, 16, v74
	v_and_b32_e32 v33, 0xffff0000, v74
	v_lshlrev_b32_e32 v34, 16, v78
	v_and_b32_e32 v35, 0xffff0000, v78
	v_lshlrev_b32_e32 v36, 16, v82
	v_and_b32_e32 v37, 0xffff0000, v82
	v_add_f32_e32 v32, v32, v34
	v_add_f32_e32 v33, v33, v35
	v_mul_f32_e32 v38, 0xbfb8aa3b, v36
	v_mul_f32_e32 v39, 0xbfb8aa3b, v37
	v_exp_f32_e32 v38, v38
	v_exp_f32_e32 v39, v39
	s_nop 0
	v_add_f32_e32 v38, 1.0, v38
	v_add_f32_e32 v39, 1.0, v39
	v_rcp_f32_e32 v38, v38
	v_rcp_f32_e32 v39, v39
	s_nop 0
	v_mul_f32_e32 v38, v36, v38
	v_mul_f32_e32 v39, v37, v39
	v_mul_f32_e32 v32, v32, v38
	v_mul_f32_e32 v33, v33, v39
	v_fmac_f32_e32 v26, v32, v32
	v_fmac_f32_e32 v26, v33, v33
	v_mul_f32_e32 v32, v32, v18
	v_mul_f32_e32 v33, v33, v19
	v_cvt_pk_bf16_f32 v42, v32, v33
	v_lshlrev_b32_e32 v32, 16, v75
	v_and_b32_e32 v33, 0xffff0000, v75
	v_lshlrev_b32_e32 v34, 16, v79
	v_and_b32_e32 v35, 0xffff0000, v79
	v_lshlrev_b32_e32 v36, 16, v83
	v_and_b32_e32 v37, 0xffff0000, v83
	v_add_f32_e32 v32, v32, v34
	v_add_f32_e32 v33, v33, v35
	v_mul_f32_e32 v38, 0xbfb8aa3b, v36
	v_mul_f32_e32 v39, 0xbfb8aa3b, v37
	v_exp_f32_e32 v38, v38
	v_exp_f32_e32 v39, v39
	s_nop 0
	v_add_f32_e32 v38, 1.0, v38
	v_add_f32_e32 v39, 1.0, v39
	v_rcp_f32_e32 v38, v38
	v_rcp_f32_e32 v39, v39
	s_nop 0
	v_mul_f32_e32 v38, v36, v38
	v_mul_f32_e32 v39, v37, v39
	v_mul_f32_e32 v32, v32, v38
	v_mul_f32_e32 v33, v33, v39
	v_fmac_f32_e32 v26, v32, v32
	v_fmac_f32_e32 v26, v33, v33
	v_mul_f32_e32 v32, v32, v20
	v_mul_f32_e32 v33, v33, v21
	v_cvt_pk_bf16_f32 v43, v32, v33
	global_store_dwordx4 v[10:11], v[40:43], off
	s_nop 1
	v_add_f32_dpp v26, v26, v26 quad_perm:[1,0,3,2] row_mask:0xf bank_mask:0xf bound_ctrl:1
	s_nop 1
	v_add_f32_dpp v26, v26, v26 quad_perm:[2,3,0,1] row_mask:0xf bank_mask:0xf bound_ctrl:1
	s_nop 1
	v_add_f32_dpp v26, v26, v26 row_half_mirror row_mask:0xf bank_mask:0xf bound_ctrl:1
	s_cmp_eq_u32 s12, 64
	s_cbranch_scc1 .Lsg_red_done_10
	s_nop 1
	v_add_f32_dpp v26, v26, v26 row_mirror row_mask:0xf bank_mask:0xf bound_ctrl:1
	v_mov_b32_e32 v31, v26
	s_nop 1
	v_permlane16_swap_b32_e32 v26, v31
	v_add_f32_e32 v26, v26, v31

.Lsg_st_done_10:
	s_or_b64 exec, exec, s[42:43]
	v_lshl_add_u64 v[10:11], v[10:11], 0, s[38:39]
	v_lshl_add_u64 v[12:13], v[12:13], 0, s[40:41]
	s_waitcnt vmcnt(28)
	v_mov_b32_e32 v26, 0
	v_lshlrev_b32_e32 v32, 16, v84
	v_and_b32_e32 v33, 0xffff0000, v84
	v_lshlrev_b32_e32 v34, 16, v88
	v_and_b32_e32 v35, 0xffff0000, v88
	v_lshlrev_b32_e32 v36, 16, v92
	v_and_b32_e32 v37, 0xffff0000, v92
	v_add_f32_e32 v32, v32, v34
	v_add_f32_e32 v33, v33, v35
	v_mul_f32_e32 v38, 0xbfb8aa3b, v36
	v_mul_f32_e32 v39, 0xbfb8aa3b, v37
	v_exp_f32_e32 v38, v38
	v_exp_f32_e32 v39, v39
	s_nop 0
	v_add_f32_e32 v38, 1.0, v38
	v_add_f32_e32 v39, 1.0, v39
	v_rcp_f32_e32 v38, v38
	v_rcp_f32_e32 v39, v39
	s_nop 0
	v_mul_f32_e32 v38, v36, v38
	v_mul_f32_e32 v39, v37, v39
	v_mul_f32_e32 v32, v32, v38
	v_mul_f32_e32 v33, v33, v39
	v_fmac_f32_e32 v26, v32, v32
	v_fmac_f32_e32 v26, v33, v33
	v_mul_f32_e32 v32, v32, v14
	v_mul_f32_e32 v33, v33, v15
	v_cvt_pk_bf16_f32 v40, v32, v33
	v_lshlrev_b32_e32 v32, 16, v85
	v_and_b32_e32 v33, 0xffff0000, v85
	v_lshlrev_b32_e32 v34, 16, v89
	v_and_b32_e32 v35, 0xffff0000, v89
	v_lshlrev_b32_e32 v36, 16, v93
	v_and_b32_e32 v37, 0xffff0000, v93
	v_add_f32_e32 v32, v32, v34
	v_add_f32_e32 v33, v33, v35
	v_mul_f32_e32 v38, 0xbfb8aa3b, v36
	v_mul_f32_e32 v39, 0xbfb8aa3b, v37
	v_exp_f32_e32 v38, v38
	v_exp_f32_e32 v39, v39
	s_nop 0
	v_add_f32_e32 v38, 1.0, v38
	v_add_f32_e32 v39, 1.0, v39
	v_rcp_f32_e32 v38, v38
	v_rcp_f32_e32 v39, v39
	s_nop 0
	v_mul_f32_e32 v38, v36, v38
	v_mul_f32_e32 v39, v37, v39
	v_mul_f32_e32 v32, v32, v38
	v_mul_f32_e32 v33, v33, v39
	v_fmac_f32_e32 v26, v32, v32
	v_fmac_f32_e32 v26, v33, v33
	v_mul_f32_e32 v32, v32, v16
	v_mul_f32_e32 v33, v33, v17
	v_cvt_pk_bf16_f32 v41, v32, v33
	v_lshlrev_b32_e32 v32, 16, v86
	v_and_b32_e32 v33, 0xffff0000, v86
	v_lshlrev_b32_e32 v34, 16, v90
	v_and_b32_e32 v35, 0xffff0000, v90
	v_lshlrev_b32_e32 v36, 16, v94
	v_and_b32_e32 v37, 0xffff0000, v94
	v_add_f32_e32 v32, v32, v34
	v_add_f32_e32 v33, v33, v35
	v_mul_f32_e32 v38, 0xbfb8aa3b, v36
	v_mul_f32_e32 v39, 0xbfb8aa3b, v37
	v_exp_f32_e32 v38, v38
	v_exp_f32_e32 v39, v39
	s_nop 0
	v_add_f32_e32 v38, 1.0, v38
	v_add_f32_e32 v39, 1.0, v39
	v_rcp_f32_e32 v38, v38
	v_rcp_f32_e32 v39, v39
	s_nop 0
	v_mul_f32_e32 v38, v36, v38
	v_mul_f32_e32 v39, v37, v39
	v_mul_f32_e32 v32, v32, v38
	v_mul_f32_e32 v33, v33, v39
	v_fmac_f32_e32 v26, v32, v32
	v_fmac_f32_e32 v26, v33, v33
	v_mul_f32_e32 v32, v32, v18
	v_mul_f32_e32 v33, v33, v19
	v_cvt_pk_bf16_f32 v42, v32, v33
	v_lshlrev_b32_e32 v32, 16, v87
	v_and_b32_e32 v33, 0xffff0000, v87
	v_lshlrev_b32_e32 v34, 16, v91
	v_and_b32_e32 v35, 0xffff0000, v91
	v_lshlrev_b32_e32 v36, 16, v95
	v_and_b32_e32 v37, 0xffff0000, v95
	v_add_f32_e32 v32, v32, v34
	v_add_f32_e32 v33, v33, v35
	v_mul_f32_e32 v38, 0xbfb8aa3b, v36
	v_mul_f32_e32 v39, 0xbfb8aa3b, v37
	v_exp_f32_e32 v38, v38
	v_exp_f32_e32 v39, v39
	s_nop 0
	v_add_f32_e32 v38, 1.0, v38
	v_add_f32_e32 v39, 1.0, v39
	v_rcp_f32_e32 v38, v38
	v_rcp_f32_e32 v39, v39
	s_nop 0
	v_mul_f32_e32 v38, v36, v38
	v_mul_f32_e32 v39, v37, v39
	v_mul_f32_e32 v32, v32, v38
	v_mul_f32_e32 v33, v33, v39
	v_fmac_f32_e32 v26, v32, v32
	v_fmac_f32_e32 v26, v33, v33
	v_mul_f32_e32 v32, v32, v20
	v_mul_f32_e32 v33, v33, v21
	v_cvt_pk_bf16_f32 v43, v32, v33
	global_store_dwordx4 v[10:11], v[40:43], off
	s_nop 1
	v_add_f32_dpp v26, v26, v26 quad_perm:[1,0,3,2] row_mask:0xf bank_mask:0xf bound_ctrl:1
	s_nop 1
	v_add_f32_dpp v26, v26, v26 quad_perm:[2,3,0,1] row_mask:0xf bank_mask:0xf bound_ctrl:1
	s_nop 1
	v_add_f32_dpp v26, v26, v26 row_half_mirror row_mask:0xf bank_mask:0xf bound_ctrl:1
	s_cmp_eq_u32 s12, 64
	s_cbranch_scc1 .Lsg_red_done_11
	s_nop 1
	v_add_f32_dpp v26, v26, v26 row_mirror row_mask:0xf bank_mask:0xf bound_ctrl:1
	v_mov_b32_e32 v31, v26
	s_nop 1
	v_permlane16_swap_b32_e32 v26, v31
	v_add_f32_e32 v26, v26, v31

.Lsg_st_done_11:
	s_or_b64 exec, exec, s[42:43]
	v_lshl_add_u64 v[10:11], v[10:11], 0, s[38:39]
	v_lshl_add_u64 v[12:13], v[12:13], 0, s[40:41]
	s_waitcnt vmcnt(25)
	v_mov_b32_e32 v26, 0
	v_lshlrev_b32_e32 v32, 16, v96
	v_and_b32_e32 v33, 0xffff0000, v96
	v_lshlrev_b32_e32 v34, 16, v100
	v_and_b32_e32 v35, 0xffff0000, v100
	v_lshlrev_b32_e32 v36, 16, v104
	v_and_b32_e32 v37, 0xffff0000, v104
	v_add_f32_e32 v32, v32, v34
	v_add_f32_e32 v33, v33, v35
	v_mul_f32_e32 v38, 0xbfb8aa3b, v36
	v_mul_f32_e32 v39, 0xbfb8aa3b, v37
	v_exp_f32_e32 v38, v38
	v_exp_f32_e32 v39, v39
	s_nop 0
	v_add_f32_e32 v38, 1.0, v38
	v_add_f32_e32 v39, 1.0, v39
	v_rcp_f32_e32 v38, v38
	v_rcp_f32_e32 v39, v39
	s_nop 0
	v_mul_f32_e32 v38, v36, v38
	v_mul_f32_e32 v39, v37, v39
	v_mul_f32_e32 v32, v32, v38
	v_mul_f32_e32 v33, v33, v39
	v_fmac_f32_e32 v26, v32, v32
	v_fmac_f32_e32 v26, v33, v33
	v_mul_f32_e32 v32, v32, v14
	v_mul_f32_e32 v33, v33, v15
	v_cvt_pk_bf16_f32 v40, v32, v33
	v_lshlrev_b32_e32 v32, 16, v97
	v_and_b32_e32 v33, 0xffff0000, v97
	v_lshlrev_b32_e32 v34, 16, v101
	v_and_b32_e32 v35, 0xffff0000, v101
	v_lshlrev_b32_e32 v36, 16, v105
	v_and_b32_e32 v37, 0xffff0000, v105
	v_add_f32_e32 v32, v32, v34
	v_add_f32_e32 v33, v33, v35
	v_mul_f32_e32 v38, 0xbfb8aa3b, v36
	v_mul_f32_e32 v39, 0xbfb8aa3b, v37
	v_exp_f32_e32 v38, v38
	v_exp_f32_e32 v39, v39
	s_nop 0
	v_add_f32_e32 v38, 1.0, v38
	v_add_f32_e32 v39, 1.0, v39
	v_rcp_f32_e32 v38, v38
	v_rcp_f32_e32 v39, v39
	s_nop 0
	v_mul_f32_e32 v38, v36, v38
	v_mul_f32_e32 v39, v37, v39
	v_mul_f32_e32 v32, v32, v38
	v_mul_f32_e32 v33, v33, v39
	v_fmac_f32_e32 v26, v32, v32
	v_fmac_f32_e32 v26, v33, v33
	v_mul_f32_e32 v32, v32, v16
	v_mul_f32_e32 v33, v33, v17
	v_cvt_pk_bf16_f32 v41, v32, v33
	v_lshlrev_b32_e32 v32, 16, v98
	v_and_b32_e32 v33, 0xffff0000, v98
	v_lshlrev_b32_e32 v34, 16, v102
	v_and_b32_e32 v35, 0xffff0000, v102
	v_lshlrev_b32_e32 v36, 16, v106
	v_and_b32_e32 v37, 0xffff0000, v106
	v_add_f32_e32 v32, v32, v34
	v_add_f32_e32 v33, v33, v35
	v_mul_f32_e32 v38, 0xbfb8aa3b, v36
	v_mul_f32_e32 v39, 0xbfb8aa3b, v37
	v_exp_f32_e32 v38, v38
	v_exp_f32_e32 v39, v39
	s_nop 0
	v_add_f32_e32 v38, 1.0, v38
	v_add_f32_e32 v39, 1.0, v39
	v_rcp_f32_e32 v38, v38
	v_rcp_f32_e32 v39, v39
	s_nop 0
	v_mul_f32_e32 v38, v36, v38
	v_mul_f32_e32 v39, v37, v39
	v_mul_f32_e32 v32, v32, v38
	v_mul_f32_e32 v33, v33, v39
	v_fmac_f32_e32 v26, v32, v32
	v_fmac_f32_e32 v26, v33, v33
	v_mul_f32_e32 v32, v32, v18
	v_mul_f32_e32 v33, v33, v19
	v_cvt_pk_bf16_f32 v42, v32, v33
	v_lshlrev_b32_e32 v32, 16, v99
	v_and_b32_e32 v33, 0xffff0000, v99
	v_lshlrev_b32_e32 v34, 16, v103
	v_and_b32_e32 v35, 0xffff0000, v103
	v_lshlrev_b32_e32 v36, 16, v107
	v_and_b32_e32 v37, 0xffff0000, v107
	v_add_f32_e32 v32, v32, v34
	v_add_f32_e32 v33, v33, v35
	v_mul_f32_e32 v38, 0xbfb8aa3b, v36
	v_mul_f32_e32 v39, 0xbfb8aa3b, v37
	v_exp_f32_e32 v38, v38
	v_exp_f32_e32 v39, v39
	s_nop 0
	v_add_f32_e32 v38, 1.0, v38
	v_add_f32_e32 v39, 1.0, v39
	v_rcp_f32_e32 v38, v38
	v_rcp_f32_e32 v39, v39
	s_nop 0
	v_mul_f32_e32 v38, v36, v38
	v_mul_f32_e32 v39, v37, v39
	v_mul_f32_e32 v32, v32, v38
	v_mul_f32_e32 v33, v33, v39
	v_fmac_f32_e32 v26, v32, v32
	v_fmac_f32_e32 v26, v33, v33
	v_mul_f32_e32 v32, v32, v20
	v_mul_f32_e32 v33, v33, v21
	v_cvt_pk_bf16_f32 v43, v32, v33
	global_store_dwordx4 v[10:11], v[40:43], off
	s_nop 1
	v_add_f32_dpp v26, v26, v26 quad_perm:[1,0,3,2] row_mask:0xf bank_mask:0xf bound_ctrl:1
	s_nop 1
	v_add_f32_dpp v26, v26, v26 quad_perm:[2,3,0,1] row_mask:0xf bank_mask:0xf bound_ctrl:1
	s_nop 1
	v_add_f32_dpp v26, v26, v26 row_half_mirror row_mask:0xf bank_mask:0xf bound_ctrl:1
	s_cmp_eq_u32 s12, 64
	s_cbranch_scc1 .Lsg_red_done_12
	s_nop 1
	v_add_f32_dpp v26, v26, v26 row_mirror row_mask:0xf bank_mask:0xf bound_ctrl:1
	v_mov_b32_e32 v31, v26
	s_nop 1
	v_permlane16_swap_b32_e32 v26, v31
	v_add_f32_e32 v26, v26, v31

.Lsg_st_done_12:
	s_or_b64 exec, exec, s[42:43]
	v_lshl_add_u64 v[10:11], v[10:11], 0, s[38:39]
	v_lshl_add_u64 v[12:13], v[12:13], 0, s[40:41]
	s_waitcnt vmcnt(22)
	v_mov_b32_e32 v26, 0
	v_lshlrev_b32_e32 v32, 16, v108
	v_and_b32_e32 v33, 0xffff0000, v108
	v_lshlrev_b32_e32 v34, 16, v112
	v_and_b32_e32 v35, 0xffff0000, v112
	v_lshlrev_b32_e32 v36, 16, v116
	v_and_b32_e32 v37, 0xffff0000, v116
	v_add_f32_e32 v32, v32, v34
	v_add_f32_e32 v33, v33, v35
	v_mul_f32_e32 v38, 0xbfb8aa3b, v36
	v_mul_f32_e32 v39, 0xbfb8aa3b, v37
	v_exp_f32_e32 v38, v38
	v_exp_f32_e32 v39, v39
	s_nop 0
	v_add_f32_e32 v38, 1.0, v38
	v_add_f32_e32 v39, 1.0, v39
	v_rcp_f32_e32 v38, v38
	v_rcp_f32_e32 v39, v39
	s_nop 0
	v_mul_f32_e32 v38, v36, v38
	v_mul_f32_e32 v39, v37, v39
	v_mul_f32_e32 v32, v32, v38
	v_mul_f32_e32 v33, v33, v39
	v_fmac_f32_e32 v26, v32, v32
	v_fmac_f32_e32 v26, v33, v33
	v_mul_f32_e32 v32, v32, v14
	v_mul_f32_e32 v33, v33, v15
	v_cvt_pk_bf16_f32 v40, v32, v33
	v_lshlrev_b32_e32 v32, 16, v109
	v_and_b32_e32 v33, 0xffff0000, v109
	v_lshlrev_b32_e32 v34, 16, v113
	v_and_b32_e32 v35, 0xffff0000, v113
	v_lshlrev_b32_e32 v36, 16, v117
	v_and_b32_e32 v37, 0xffff0000, v117
	v_add_f32_e32 v32, v32, v34
	v_add_f32_e32 v33, v33, v35
	v_mul_f32_e32 v38, 0xbfb8aa3b, v36
	v_mul_f32_e32 v39, 0xbfb8aa3b, v37
	v_exp_f32_e32 v38, v38
	v_exp_f32_e32 v39, v39
	s_nop 0
	v_add_f32_e32 v38, 1.0, v38
	v_add_f32_e32 v39, 1.0, v39
	v_rcp_f32_e32 v38, v38
	v_rcp_f32_e32 v39, v39
	s_nop 0
	v_mul_f32_e32 v38, v36, v38
	v_mul_f32_e32 v39, v37, v39
	v_mul_f32_e32 v32, v32, v38
	v_mul_f32_e32 v33, v33, v39
	v_fmac_f32_e32 v26, v32, v32
	v_fmac_f32_e32 v26, v33, v33
	v_mul_f32_e32 v32, v32, v16
	v_mul_f32_e32 v33, v33, v17
	v_cvt_pk_bf16_f32 v41, v32, v33
	v_lshlrev_b32_e32 v32, 16, v110
	v_and_b32_e32 v33, 0xffff0000, v110
	v_lshlrev_b32_e32 v34, 16, v114
	v_and_b32_e32 v35, 0xffff0000, v114
	v_lshlrev_b32_e32 v36, 16, v118
	v_and_b32_e32 v37, 0xffff0000, v118
	v_add_f32_e32 v32, v32, v34
	v_add_f32_e32 v33, v33, v35
	v_mul_f32_e32 v38, 0xbfb8aa3b, v36
	v_mul_f32_e32 v39, 0xbfb8aa3b, v37
	v_exp_f32_e32 v38, v38
	v_exp_f32_e32 v39, v39
	s_nop 0
	v_add_f32_e32 v38, 1.0, v38
	v_add_f32_e32 v39, 1.0, v39
	v_rcp_f32_e32 v38, v38
	v_rcp_f32_e32 v39, v39
	s_nop 0
	v_mul_f32_e32 v38, v36, v38
	v_mul_f32_e32 v39, v37, v39
	v_mul_f32_e32 v32, v32, v38
	v_mul_f32_e32 v33, v33, v39
	v_fmac_f32_e32 v26, v32, v32
	v_fmac_f32_e32 v26, v33, v33
	v_mul_f32_e32 v32, v32, v18
	v_mul_f32_e32 v33, v33, v19
	v_cvt_pk_bf16_f32 v42, v32, v33
	v_lshlrev_b32_e32 v32, 16, v111
	v_and_b32_e32 v33, 0xffff0000, v111
	v_lshlrev_b32_e32 v34, 16, v115
	v_and_b32_e32 v35, 0xffff0000, v115
	v_lshlrev_b32_e32 v36, 16, v119
	v_and_b32_e32 v37, 0xffff0000, v119
	v_add_f32_e32 v32, v32, v34
	v_add_f32_e32 v33, v33, v35
	v_mul_f32_e32 v38, 0xbfb8aa3b, v36
	v_mul_f32_e32 v39, 0xbfb8aa3b, v37
	v_exp_f32_e32 v38, v38
	v_exp_f32_e32 v39, v39
	s_nop 0
	v_add_f32_e32 v38, 1.0, v38
	v_add_f32_e32 v39, 1.0, v39
	v_rcp_f32_e32 v38, v38
	v_rcp_f32_e32 v39, v39
	s_nop 0
	v_mul_f32_e32 v38, v36, v38
	v_mul_f32_e32 v39, v37, v39
	v_mul_f32_e32 v32, v32, v38
	v_mul_f32_e32 v33, v33, v39
	v_fmac_f32_e32 v26, v32, v32
	v_fmac_f32_e32 v26, v33, v33
	v_mul_f32_e32 v32, v32, v20
	v_mul_f32_e32 v33, v33, v21
	v_cvt_pk_bf16_f32 v43, v32, v33
	global_store_dwordx4 v[10:11], v[40:43], off
	s_nop 1
	v_add_f32_dpp v26, v26, v26 quad_perm:[1,0,3,2] row_mask:0xf bank_mask:0xf bound_ctrl:1
	s_nop 1
	v_add_f32_dpp v26, v26, v26 quad_perm:[2,3,0,1] row_mask:0xf bank_mask:0xf bound_ctrl:1
	s_nop 1
	v_add_f32_dpp v26, v26, v26 row_half_mirror row_mask:0xf bank_mask:0xf bound_ctrl:1
	s_cmp_eq_u32 s12, 64
	s_cbranch_scc1 .Lsg_red_done_13
	s_nop 1
	v_add_f32_dpp v26, v26, v26 row_mirror row_mask:0xf bank_mask:0xf bound_ctrl:1
	v_mov_b32_e32 v31, v26
	s_nop 1
	v_permlane16_swap_b32_e32 v26, v31
	v_add_f32_e32 v26, v26, v31

.Lsg_st_done_13:
	s_or_b64 exec, exec, s[42:43]
	v_lshl_add_u64 v[10:11], v[10:11], 0, s[38:39]
	v_lshl_add_u64 v[12:13], v[12:13], 0, s[40:41]
	s_waitcnt vmcnt(19)
	v_mov_b32_e32 v26, 0
	v_lshlrev_b32_e32 v32, 16, v120
	v_and_b32_e32 v33, 0xffff0000, v120
	v_lshlrev_b32_e32 v34, 16, v124
	v_and_b32_e32 v35, 0xffff0000, v124
	v_lshlrev_b32_e32 v36, 16, v128
	v_and_b32_e32 v37, 0xffff0000, v128
	v_add_f32_e32 v32, v32, v34
	v_add_f32_e32 v33, v33, v35
	v_mul_f32_e32 v38, 0xbfb8aa3b, v36
	v_mul_f32_e32 v39, 0xbfb8aa3b, v37
	v_exp_f32_e32 v38, v38
	v_exp_f32_e32 v39, v39
	s_nop 0
	v_add_f32_e32 v38, 1.0, v38
	v_add_f32_e32 v39, 1.0, v39
	v_rcp_f32_e32 v38, v38
	v_rcp_f32_e32 v39, v39
	s_nop 0
	v_mul_f32_e32 v38, v36, v38
	v_mul_f32_e32 v39, v37, v39
	v_mul_f32_e32 v32, v32, v38
	v_mul_f32_e32 v33, v33, v39
	v_fmac_f32_e32 v26, v32, v32
	v_fmac_f32_e32 v26, v33, v33
	v_mul_f32_e32 v32, v32, v14
	v_mul_f32_e32 v33, v33, v15
	v_cvt_pk_bf16_f32 v40, v32, v33
	v_lshlrev_b32_e32 v32, 16, v121
	v_and_b32_e32 v33, 0xffff0000, v121
	v_lshlrev_b32_e32 v34, 16, v125
	v_and_b32_e32 v35, 0xffff0000, v125
	v_lshlrev_b32_e32 v36, 16, v129
	v_and_b32_e32 v37, 0xffff0000, v129
	v_add_f32_e32 v32, v32, v34
	v_add_f32_e32 v33, v33, v35
	v_mul_f32_e32 v38, 0xbfb8aa3b, v36
	v_mul_f32_e32 v39, 0xbfb8aa3b, v37
	v_exp_f32_e32 v38, v38
	v_exp_f32_e32 v39, v39
	s_nop 0
	v_add_f32_e32 v38, 1.0, v38
	v_add_f32_e32 v39, 1.0, v39
	v_rcp_f32_e32 v38, v38
	v_rcp_f32_e32 v39, v39
	s_nop 0
	v_mul_f32_e32 v38, v36, v38
	v_mul_f32_e32 v39, v37, v39
	v_mul_f32_e32 v32, v32, v38
	v_mul_f32_e32 v33, v33, v39
	v_fmac_f32_e32 v26, v32, v32
	v_fmac_f32_e32 v26, v33, v33
	v_mul_f32_e32 v32, v32, v16
	v_mul_f32_e32 v33, v33, v17
	v_cvt_pk_bf16_f32 v41, v32, v33
	v_lshlrev_b32_e32 v32, 16, v122
	v_and_b32_e32 v33, 0xffff0000, v122
	v_lshlrev_b32_e32 v34, 16, v126
	v_and_b32_e32 v35, 0xffff0000, v126
	v_lshlrev_b32_e32 v36, 16, v130
	v_and_b32_e32 v37, 0xffff0000, v130
	v_add_f32_e32 v32, v32, v34
	v_add_f32_e32 v33, v33, v35
	v_mul_f32_e32 v38, 0xbfb8aa3b, v36
	v_mul_f32_e32 v39, 0xbfb8aa3b, v37
	v_exp_f32_e32 v38, v38
	v_exp_f32_e32 v39, v39
	s_nop 0
	v_add_f32_e32 v38, 1.0, v38
	v_add_f32_e32 v39, 1.0, v39
	v_rcp_f32_e32 v38, v38
	v_rcp_f32_e32 v39, v39
	s_nop 0
	v_mul_f32_e32 v38, v36, v38
	v_mul_f32_e32 v39, v37, v39
	v_mul_f32_e32 v32, v32, v38
	v_mul_f32_e32 v33, v33, v39
	v_fmac_f32_e32 v26, v32, v32
	v_fmac_f32_e32 v26, v33, v33
	v_mul_f32_e32 v32, v32, v18
	v_mul_f32_e32 v33, v33, v19
	v_cvt_pk_bf16_f32 v42, v32, v33
	v_lshlrev_b32_e32 v32, 16, v123
	v_and_b32_e32 v33, 0xffff0000, v123
	v_lshlrev_b32_e32 v34, 16, v127
	v_and_b32_e32 v35, 0xffff0000, v127
	v_lshlrev_b32_e32 v36, 16, v131
	v_and_b32_e32 v37, 0xffff0000, v131
	v_add_f32_e32 v32, v32, v34
	v_add_f32_e32 v33, v33, v35
	v_mul_f32_e32 v38, 0xbfb8aa3b, v36
	v_mul_f32_e32 v39, 0xbfb8aa3b, v37
	v_exp_f32_e32 v38, v38
	v_exp_f32_e32 v39, v39
	s_nop 0
	v_add_f32_e32 v38, 1.0, v38
	v_add_f32_e32 v39, 1.0, v39
	v_rcp_f32_e32 v38, v38
	v_rcp_f32_e32 v39, v39
	s_nop 0
	v_mul_f32_e32 v38, v36, v38
	v_mul_f32_e32 v39, v37, v39
	v_mul_f32_e32 v32, v32, v38
	v_mul_f32_e32 v33, v33, v39
	v_fmac_f32_e32 v26, v32, v32
	v_fmac_f32_e32 v26, v33, v33
	v_mul_f32_e32 v32, v32, v20
	v_mul_f32_e32 v33, v33, v21
	v_cvt_pk_bf16_f32 v43, v32, v33
	global_store_dwordx4 v[10:11], v[40:43], off
	s_nop 1
	v_add_f32_dpp v26, v26, v26 quad_perm:[1,0,3,2] row_mask:0xf bank_mask:0xf bound_ctrl:1
	s_nop 1
	v_add_f32_dpp v26, v26, v26 quad_perm:[2,3,0,1] row_mask:0xf bank_mask:0xf bound_ctrl:1
	s_nop 1
	v_add_f32_dpp v26, v26, v26 row_half_mirror row_mask:0xf bank_mask:0xf bound_ctrl:1
	s_cmp_eq_u32 s12, 64
	s_cbranch_scc1 .Lsg_red_done_14
	s_nop 1
	v_add_f32_dpp v26, v26, v26 row_mirror row_mask:0xf bank_mask:0xf bound_ctrl:1
	v_mov_b32_e32 v31, v26
	s_nop 1
	v_permlane16_swap_b32_e32 v26, v31
	v_add_f32_e32 v26, v26, v31

.Lsg_st_done_14:
	s_or_b64 exec, exec, s[42:43]
	v_lshl_add_u64 v[10:11], v[10:11], 0, s[38:39]
	v_lshl_add_u64 v[12:13], v[12:13], 0, s[40:41]
	s_waitcnt vmcnt(16)
	v_mov_b32_e32 v26, 0
	v_lshlrev_b32_e32 v32, 16, v132
	v_and_b32_e32 v33, 0xffff0000, v132
	v_lshlrev_b32_e32 v34, 16, v136
	v_and_b32_e32 v35, 0xffff0000, v136
	v_lshlrev_b32_e32 v36, 16, v140
	v_and_b32_e32 v37, 0xffff0000, v140
	v_add_f32_e32 v32, v32, v34
	v_add_f32_e32 v33, v33, v35
	v_mul_f32_e32 v38, 0xbfb8aa3b, v36
	v_mul_f32_e32 v39, 0xbfb8aa3b, v37
	v_exp_f32_e32 v38, v38
	v_exp_f32_e32 v39, v39
	s_nop 0
	v_add_f32_e32 v38, 1.0, v38
	v_add_f32_e32 v39, 1.0, v39
	v_rcp_f32_e32 v38, v38
	v_rcp_f32_e32 v39, v39
	s_nop 0
	v_mul_f32_e32 v38, v36, v38
	v_mul_f32_e32 v39, v37, v39
	v_mul_f32_e32 v32, v32, v38
	v_mul_f32_e32 v33, v33, v39
	v_fmac_f32_e32 v26, v32, v32
	v_fmac_f32_e32 v26, v33, v33
	v_mul_f32_e32 v32, v32, v14
	v_mul_f32_e32 v33, v33, v15
	v_cvt_pk_bf16_f32 v40, v32, v33
	v_lshlrev_b32_e32 v32, 16, v133
	v_and_b32_e32 v33, 0xffff0000, v133
	v_lshlrev_b32_e32 v34, 16, v137
	v_and_b32_e32 v35, 0xffff0000, v137
	v_lshlrev_b32_e32 v36, 16, v141
	v_and_b32_e32 v37, 0xffff0000, v141
	v_add_f32_e32 v32, v32, v34
	v_add_f32_e32 v33, v33, v35
	v_mul_f32_e32 v38, 0xbfb8aa3b, v36
	v_mul_f32_e32 v39, 0xbfb8aa3b, v37
	v_exp_f32_e32 v38, v38
	v_exp_f32_e32 v39, v39
	s_nop 0
	v_add_f32_e32 v38, 1.0, v38
	v_add_f32_e32 v39, 1.0, v39
	v_rcp_f32_e32 v38, v38
	v_rcp_f32_e32 v39, v39
	s_nop 0
	v_mul_f32_e32 v38, v36, v38
	v_mul_f32_e32 v39, v37, v39
	v_mul_f32_e32 v32, v32, v38
	v_mul_f32_e32 v33, v33, v39
	v_fmac_f32_e32 v26, v32, v32
	v_fmac_f32_e32 v26, v33, v33
	v_mul_f32_e32 v32, v32, v16
	v_mul_f32_e32 v33, v33, v17
	v_cvt_pk_bf16_f32 v41, v32, v33
	v_lshlrev_b32_e32 v32, 16, v134
	v_and_b32_e32 v33, 0xffff0000, v134
	v_lshlrev_b32_e32 v34, 16, v138
	v_and_b32_e32 v35, 0xffff0000, v138
	v_lshlrev_b32_e32 v36, 16, v142
	v_and_b32_e32 v37, 0xffff0000, v142
	v_add_f32_e32 v32, v32, v34
	v_add_f32_e32 v33, v33, v35
	v_mul_f32_e32 v38, 0xbfb8aa3b, v36
	v_mul_f32_e32 v39, 0xbfb8aa3b, v37
	v_exp_f32_e32 v38, v38
	v_exp_f32_e32 v39, v39
	s_nop 0
	v_add_f32_e32 v38, 1.0, v38
	v_add_f32_e32 v39, 1.0, v39
	v_rcp_f32_e32 v38, v38
	v_rcp_f32_e32 v39, v39
	s_nop 0
	v_mul_f32_e32 v38, v36, v38
	v_mul_f32_e32 v39, v37, v39
	v_mul_f32_e32 v32, v32, v38
	v_mul_f32_e32 v33, v33, v39
	v_fmac_f32_e32 v26, v32, v32
	v_fmac_f32_e32 v26, v33, v33
	v_mul_f32_e32 v32, v32, v18
	v_mul_f32_e32 v33, v33, v19
	v_cvt_pk_bf16_f32 v42, v32, v33
	v_lshlrev_b32_e32 v32, 16, v135
	v_and_b32_e32 v33, 0xffff0000, v135
	v_lshlrev_b32_e32 v34, 16, v139
	v_and_b32_e32 v35, 0xffff0000, v139
	v_lshlrev_b32_e32 v36, 16, v143
	v_and_b32_e32 v37, 0xffff0000, v143
	v_add_f32_e32 v32, v32, v34
	v_add_f32_e32 v33, v33, v35
	v_mul_f32_e32 v38, 0xbfb8aa3b, v36
	v_mul_f32_e32 v39, 0xbfb8aa3b, v37
	v_exp_f32_e32 v38, v38
	v_exp_f32_e32 v39, v39
	s_nop 0
	v_add_f32_e32 v38, 1.0, v38
	v_add_f32_e32 v39, 1.0, v39
	v_rcp_f32_e32 v38, v38
	v_rcp_f32_e32 v39, v39
	s_nop 0
	v_mul_f32_e32 v38, v36, v38
	v_mul_f32_e32 v39, v37, v39
	v_mul_f32_e32 v32, v32, v38
	v_mul_f32_e32 v33, v33, v39
	v_fmac_f32_e32 v26, v32, v32
	v_fmac_f32_e32 v26, v33, v33
	v_mul_f32_e32 v32, v32, v20
	v_mul_f32_e32 v33, v33, v21
	v_cvt_pk_bf16_f32 v43, v32, v33
	global_store_dwordx4 v[10:11], v[40:43], off
	s_nop 1
	v_add_f32_dpp v26, v26, v26 quad_perm:[1,0,3,2] row_mask:0xf bank_mask:0xf bound_ctrl:1
	s_nop 1
	v_add_f32_dpp v26, v26, v26 quad_perm:[2,3,0,1] row_mask:0xf bank_mask:0xf bound_ctrl:1
	s_nop 1
	v_add_f32_dpp v26, v26, v26 row_half_mirror row_mask:0xf bank_mask:0xf bound_ctrl:1
	s_cmp_eq_u32 s12, 64
	s_cbranch_scc1 .Lsg_red_done_15
	s_nop 1
	v_add_f32_dpp v26, v26, v26 row_mirror row_mask:0xf bank_mask:0xf bound_ctrl:1
	v_mov_b32_e32 v31, v26
	s_nop 1
	v_permlane16_swap_b32_e32 v26, v31
	v_add_f32_e32 v26, v26, v31

.Lsg_st_done_15:
	s_or_b64 exec, exec, s[42:43]
	v_lshl_add_u64 v[10:11], v[10:11], 0, s[38:39]
	v_lshl_add_u64 v[12:13], v[12:13], 0, s[40:41]
	s_add_i32 s4, s4, s74
	s_cmpk_lt_i32 s4, 0x100
	s_cbranch_scc1 .Lsg_bun
